# SwiGLU / plain GEMM epilogues: row-statistic loads issued before the K-loop (their wait no longer drains the in-flight next-tile LDS-DMA at epilogue start)
# speedup vs baseline: 1.0106x; 1.0026x over previous
; #define PG8_BAR __builtin_amdgcn_s_barrier()
; template <class Epi>
; __device__ __forceinline__ void gemm_phase(LAS unsigned char* lds, const Gemm g, const StaticOrder& S, const Epi& E) {
;     ...
;     for (;;) {
;         const bool has_next = S.next(ui + 1, nxt);
;         const char* nA = has_next ? (const char*)g.A + (size_t)nxt.pm * tstep : cA; const char* nB = has_next ? (const char*)g.Bt + (size_t)nxt.pn * tstep : cB;
;         for (int t = 0; t < nt; t += 2) {
;             const bool last = (t == nt - 2);
;             const char* a1 = cA + (size_t)(t + 1) * kstep;
;             const char* a2 = last ? nA : cA + (size_t)(t + 2) * kstep; const char* b2 = last ? nB : cB + (size_t)(t + 2) * kstep;
;             const char* a3 = a2 + kstep; const char* b3 = b2 + kstep;
;             PG8_LDB(B0, 0, 0); PG8_SCHED; PG8_LDA(At, 0, 0); PG8_STAGE(PG8_SA(1, 1), a1 + hstep, voffA);
;             PG8_WAIT_L(8); PG8_BAR; PG8_WAIT_L(0); PG8_MMA(0, 0, At, B0); PG8_BAR; PG8_SCHED;
;             PG8_LDB(B1, 0, 1); PG8_STAGE(PG8_SB(0, 0), b2, voffB);
;             PG8_BAR; PG8_WAIT_L(0); PG8_MMA(0, 1, At, B1); PG8_BAR;
;             PG8_LDA(At, 0, 1); PG8_STAGE(PG8_SA(0, 0), a2, voffA);
;             PG8_BAR; PG8_WAIT_L(0); PG8_MMA(1, 0, At, B0); PG8_BAR; PG8_SCHED;
;             PG8_STAGE(PG8_SB(0, 1), b2 + hstep, voffB);
;             PG8_WAIT_V(6); PG8_BAR; PG8_MMA(1, 1, At, B1); PG8_BAR;
;             PG8_LDB(B0, 1, 0); PG8_SCHED; PG8_LDA(At, 1, 0); PG8_STAGE(PG8_SA(0, 1), a2 + hstep, voffA);
;             PG8_WAIT_L(8); PG8_BAR; PG8_WAIT_L(0); PG8_MMA(0, 0, At, B0); PG8_BAR; PG8_SCHED;
;             PG8_LDB(B1, 1, 1); PG8_STAGE(PG8_SB(1, 0), b3, voffB);
;             PG8_BAR; PG8_WAIT_L(0); PG8_MMA(0, 1, At, B1); PG8_BAR;
;             PG8_LDA(At, 1, 1); PG8_STAGE(PG8_SA(1, 0), a3, voffA);
;             PG8_BAR; PG8_WAIT_L(0); PG8_MMA(1, 0, At, B0); PG8_BAR; PG8_SCHED;
;             PG8_STAGE(PG8_SB(1, 1), b3 + hstep, voffB);
;             PG8_WAIT_V(6); PG8_BAR; PG8_MMA(1, 1, At, B1); PG8_BAR;
;         }
;         E(acc, cur, wr, wc, fr, fq);
;         if (!has_next) break;
; #pragma unroll
;         for (int a = 0; a < 2; ++a)
; #pragma unroll
;             for (int b = 0; b < 2; ++b)
; #pragma unroll
;                 for (int m = 0; m < 4; ++m)
; #pragma unroll
;                     for (int n = 0; n < 2; ++n) acc[a][b][m][n] = (f32x4){0.f, 0.f, 0.f, 0.f};
.LBB0_63:
	v_mov_b64_e32 v[2:3], s[42:43]
	s_ashr_i32 s49, s48, 31
	v_cmp_lt_i64_e32 vcc, s[50:51], v[2:3]
	s_lshl_b64 s[50:51], s[48:49], 20
	v_readlane_b32 s52, v254, 8
	v_readlane_b32 s53, v254, 9
	s_add_u32 s50, s52, s50
	s_addc_u32 s51, s53, s51
	s_and_b64 s[52:53], vcc, exec
	s_cselect_b32 s49, s51, s57
	s_cselect_b32 s81, s50, s56
	s_ashr_i32 s47, s46, 31
	s_lshl_b64 s[52:53], s[46:47], 20
	s_add_u32 s52, s65, s52
	s_addc_u32 s53, s68, s53
	s_and_b64 s[60:61], vcc, exec
	s_cselect_b32 s47, s53, s59
	s_cselect_b32 s82, s52, s58
	s_add_u32 s56, s56, 0x80080
	s_addc_u32 s57, s57, 0
	s_add_u32 s83, s58, 0x100
	v_mov_b32_e32 v2, 0
	s_addc_u32 s84, s59, 0
	s_mov_b32 s85, -2
	v_mov_b32_e32 v3, v2
	v_mov_b32_e32 v4, v2
	v_mov_b32_e32 v5, v2
	v_mov_b32_e32 v6, v2
	v_mov_b32_e32 v7, v2
	v_mov_b32_e32 v8, v2
	v_mov_b32_e32 v9, v2
	v_mov_b32_e32 v10, v2
	v_mov_b32_e32 v11, v2
	v_mov_b32_e32 v12, v2
	v_mov_b32_e32 v13, v2
	v_mov_b32_e32 v18, v2
	v_mov_b32_e32 v19, v2
	v_mov_b32_e32 v20, v2
	v_mov_b32_e32 v21, v2
	s_waitcnt vmcnt(0)
	v_mov_b32_e32 v26, v2
	v_mov_b32_e32 v27, v2
	v_mov_b32_e32 v28, v2
	v_mov_b32_e32 v29, v2
	v_mov_b32_e32 v34, v2
	v_mov_b32_e32 v35, v2
	v_mov_b32_e32 v36, v2
	v_mov_b32_e32 v37, v2
	v_mov_b32_e32 v42, v2
	v_mov_b32_e32 v43, v2
	v_mov_b32_e32 v44, v2
	v_mov_b32_e32 v45, v2
	v_mov_b32_e32 v50, v2
	v_mov_b32_e32 v51, v2
	v_mov_b32_e32 v52, v2
	v_mov_b32_e32 v53, v2
	v_mov_b32_e32 v14, v2
	v_mov_b32_e32 v15, v2
	v_mov_b32_e32 v16, v2
	v_mov_b32_e32 v17, v2
	v_mov_b32_e32 v22, v2
	v_mov_b32_e32 v23, v2
	v_mov_b32_e32 v24, v2
	v_mov_b32_e32 v25, v2
	v_mov_b32_e32 v30, v2
	v_mov_b32_e32 v31, v2
	v_mov_b32_e32 v32, v2
	v_mov_b32_e32 v33, v2
	v_mov_b32_e32 v38, v2
	v_mov_b32_e32 v39, v2
	v_mov_b32_e32 v40, v2
	v_mov_b32_e32 v41, v2
	v_mov_b32_e32 v46, v2
	v_mov_b32_e32 v47, v2
	v_mov_b32_e32 v48, v2
	v_mov_b32_e32 v49, v2
	v_mov_b32_e32 v54, v2
	v_mov_b32_e32 v55, v2
	v_mov_b32_e32 v56, v2
	v_mov_b32_e32 v57, v2
	v_mov_b32_e32 v58, v2
	v_mov_b32_e32 v59, v2
	v_mov_b32_e32 v60, v2
	v_mov_b32_e32 v61, v2
	v_mov_b32_e32 v62, v2
	v_mov_b32_e32 v63, v2
	v_mov_b32_e32 v64, v2
	v_mov_b32_e32 v65, v2
	v_mov_b32_e32 v66, v2
	v_mov_b32_e32 v67, v2
	v_mov_b32_e32 v68, v2
	v_mov_b32_e32 v69, v2
	v_mov_b32_e32 v70, v2
	v_mov_b32_e32 v71, v2
	v_mov_b32_e32 v72, v2
	v_mov_b32_e32 v73, v2
	v_mov_b32_e32 v82, v2
	v_mov_b32_e32 v83, v2
	v_mov_b32_e32 v84, v2
	v_mov_b32_e32 v85, v2
	v_mov_b32_e32 v86, v2
	v_mov_b32_e32 v87, v2
	v_mov_b32_e32 v88, v2
	v_mov_b32_e32 v89, v2
	v_mov_b32_e32 v98, v2
	v_mov_b32_e32 v99, v2
	v_mov_b32_e32 v100, v2
	v_mov_b32_e32 v101, v2
	v_mov_b32_e32 v102, v2
	v_mov_b32_e32 v103, v2
	v_mov_b32_e32 v104, v2
	v_mov_b32_e32 v105, v2
	v_mov_b32_e32 v114, v2
	v_mov_b32_e32 v115, v2
	v_mov_b32_e32 v116, v2
	v_mov_b32_e32 v117, v2
	v_mov_b32_e32 v118, v2
	v_mov_b32_e32 v119, v2
	v_mov_b32_e32 v120, v2
	v_mov_b32_e32 v121, v2
	v_mov_b32_e32 v74, v2
	v_mov_b32_e32 v75, v2
	v_mov_b32_e32 v76, v2
	v_mov_b32_e32 v77, v2
	v_mov_b32_e32 v78, v2
	v_mov_b32_e32 v79, v2
	v_mov_b32_e32 v80, v2
	v_mov_b32_e32 v81, v2
	v_mov_b32_e32 v90, v2
	v_mov_b32_e32 v91, v2
	v_mov_b32_e32 v92, v2
	v_mov_b32_e32 v93, v2
	v_mov_b32_e32 v94, v2
	v_mov_b32_e32 v95, v2
	v_mov_b32_e32 v96, v2
	v_mov_b32_e32 v97, v2
	v_mov_b32_e32 v106, v2
	v_mov_b32_e32 v107, v2
	v_mov_b32_e32 v108, v2
	v_mov_b32_e32 v109, v2
	v_mov_b32_e32 v110, v2
	v_mov_b32_e32 v111, v2
	v_mov_b32_e32 v112, v2
	v_mov_b32_e32 v113, v2
	v_mov_b32_e32 v122, v2
	v_mov_b32_e32 v123, v2
	v_mov_b32_e32 v124, v2
	v_mov_b32_e32 v125, v2
	v_mov_b32_e32 v126, v2
	v_mov_b32_e32 v127, v2
	v_mov_b32_e32 v128, v2
	v_mov_b32_e32 v129, v2
	s_lshl_b32 s98, s54, 8
	s_add_i32 s98, s98, s75
	v_or_b32_e32 v154, s98, v145
	v_ashrrev_i32_e32 v155, 31, v154
	v_lshl_add_u64 v[154:155], v[154:155], 2, s[2:3]
	global_load_dword v140, v[154:155], off
	v_add_u32_e32 v154, s98, v147
	v_ashrrev_i32_e32 v155, 31, v154
	v_lshl_add_u64 v[154:155], v[154:155], 2, s[2:3]
	global_load_dword v142, v[154:155], off
	v_add_u32_e32 v202, 0x10000, v143
	ds_read_b128 v[154:157], v202
	ds_read_b128 v[158:161], v202 offset:1024
	ds_read_b128 v[162:165], v202 offset:2048
	ds_read_b128 v[166:169], v202 offset:3072
.LBB0_64:
	s_add_u32 s58, s56, 0xfff80080
	s_addc_u32 s59, s57, -1
	s_add_i32 s86, 0, 0x10000
	s_cmp_eq_u32 s85, 28
	s_cselect_b32 s61, s49, s59
	s_cselect_b32 s60, s81, s58
	s_cselect_b32 s59, s47, s84
	s_cselect_b32 s58, s82, s83
	s_add_i32 m0, s55, 0xc000
	ds_read_b128 v[170:173], v151
	ds_read_b128 v[174:177], v151 offset:1024
	ds_read_b128 v[178:181], v151 offset:2048
	ds_read_b128 v[182:185], v151 offset:3072
	ds_read_b128 v[186:189], v151 offset:4096
	ds_read_b128 v[190:193], v151 offset:5120
	ds_read_b128 v[194:197], v151 offset:6144
	ds_read_b128 v[198:201], v151 offset:7168
	global_load_lds_dwordx4 v136, s[56:57]
	s_add_i32 m0, s55, 0xe000
	s_waitcnt lgkmcnt(8)
	global_load_lds_dwordx4 v138, s[56:57]
	s_barrier
	s_waitcnt lgkmcnt(0)
	v_mfma_f32_16x16x32_bf16 v[126:129], v[154:157], v[170:173], v[126:129]
	v_mfma_f32_16x16x32_bf16 v[122:125], v[162:165], v[170:173], v[122:125]
	v_mfma_f32_16x16x32_bf16 v[110:113], v[154:157], v[178:181], v[110:113]
	v_mfma_f32_16x16x32_bf16 v[106:109], v[162:165], v[178:181], v[106:109]
	v_mfma_f32_16x16x32_bf16 v[94:97], v[154:157], v[186:189], v[94:97]
	v_mfma_f32_16x16x32_bf16 v[90:93], v[162:165], v[186:189], v[90:93]
	v_mfma_f32_16x16x32_bf16 v[78:81], v[154:157], v[194:197], v[78:81]
	v_mfma_f32_16x16x32_bf16 v[74:77], v[162:165], v[194:197], v[74:77]
	v_mfma_f32_16x16x32_bf16 v[126:129], v[158:161], v[174:177], v[126:129]
	v_mfma_f32_16x16x32_bf16 v[122:125], v[166:169], v[174:177], v[122:125]
	v_mfma_f32_16x16x32_bf16 v[110:113], v[158:161], v[182:185], v[110:113]
	v_mfma_f32_16x16x32_bf16 v[106:109], v[166:169], v[182:185], v[106:109]
	v_mfma_f32_16x16x32_bf16 v[94:97], v[158:161], v[190:193], v[94:97]
	v_mfma_f32_16x16x32_bf16 v[90:93], v[166:169], v[190:193], v[90:93]
	v_mfma_f32_16x16x32_bf16 v[78:81], v[158:161], v[198:201], v[78:81]
	v_mfma_f32_16x16x32_bf16 v[74:77], v[166:169], v[198:201], v[74:77]
	s_barrier
; #define PG8_STAGE(bufoff, gbase, voff) do { _Pragma("unroll") for (int _i = 0; _i < 2; ++_i) \
;         __builtin_amdgcn_global_load_lds((const unsigned*)((const char*)(gbase) + (voff)[_i]), (LAS unsigned*)(lds + (bufoff) + ldsw + _i * 8192), 16, 0, 0); } while (0)
; #define PG8_LDA(dst, b, h) do { _Pragma("unroll") for (int m = 0; m < 4; ++m) _Pragma("unroll") for (int k = 0; k < 2; ++k) dst[m][k] = *(const LAS bf16x8*)(lds + PG8_SA(b, h) + aoff + m * 2048 + k * 1024); } while (0)
; #define PG8_LDB(dst, b, h) do { _Pragma("unroll") for (int n = 0; n < 2; ++n) _Pragma("unroll") for (int k = 0; k < 2; ++k) dst[n][k] = *(const LAS bf16x8*)(lds + PG8_SB(b, h) + boff + n * 2048 + k * 1024); } while (0)
; #define PG8_MMA(ai, bj, At, Bt) do { __builtin_amdgcn_s_setprio(1); _Pragma("unroll") for (int m = 0; m < 4; ++m) _Pragma("unroll") for (int n = 0; n < 2; ++n) _Pragma("unroll") for (int k = 0; k < 2; ++k) \
;         acc[ai][bj][m][n] = __builtin_amdgcn_mfma_f32_16x16x32_bf16(Bt[n][k], At[m][k], acc[ai][bj][m][n], 0, 0, 0); __builtin_amdgcn_s_setprio(0); } while (0)
; #define PG8_WAIT_V(n) asm volatile("s_waitcnt vmcnt(" #n ")" ::: "memory")
; #define PG8_WAIT_L(n) asm volatile("s_waitcnt lgkmcnt(" #n ")" ::: "memory")
; #define PG8_BAR __builtin_amdgcn_s_barrier()
; #define PG8_SCHED __builtin_amdgcn_sched_barrier(0)
; template <class Epi>
; __device__ __forceinline__ void gemm_phase(LAS unsigned char* lds, const Gemm g, const StaticOrder& S, const Epi& E) {
;     ...
;             PG8_LDB(B1, 0, 1); PG8_STAGE(PG8_SB(0, 0), b2, voffB);
;             PG8_BAR; PG8_WAIT_L(0); PG8_MMA(0, 1, At, B1); PG8_BAR;
;             PG8_LDA(At, 0, 1); PG8_STAGE(PG8_SA(0, 0), a2, voffA);
;             PG8_BAR; PG8_WAIT_L(0); PG8_MMA(1, 0, At, B0); PG8_BAR; PG8_SCHED;
;             PG8_STAGE(PG8_SB(0, 1), b2 + hstep, voffB);
;             PG8_WAIT_V(6); PG8_BAR; PG8_MMA(1, 1, At, B1); PG8_BAR;
;             PG8_LDB(B0, 1, 0); PG8_SCHED; PG8_LDA(At, 1, 0); PG8_STAGE(PG8_SA(0, 1), a2 + hstep, voffA);
;             PG8_WAIT_L(8); PG8_BAR; PG8_WAIT_L(0); PG8_MMA(0, 0, At, B0); PG8_BAR; PG8_SCHED;
;             PG8_LDB(B1, 1, 1); PG8_STAGE(PG8_SB(1, 0), b3, voffB);
	s_add_i32 s86, s86, s69
	s_add_u32 s98, s58, s22
	s_addc_u32 s99, s59, s23
	s_mov_b32 m0, s86
	ds_read_b128 v[208:211], v202 offset:16384
	ds_read_b128 v[212:215], v202 offset:17408
	ds_read_b128 v[216:219], v202 offset:18432
	ds_read_b128 v[220:223], v202 offset:19456
	global_load_lds_dwordx4 v0, s[58:59]
	s_add_i32 m0, s86, 0x2000
	s_add_i32 s88, 0, 0x14000
	global_load_lds_dwordx4 v130, s[58:59]
	s_barrier
	s_waitcnt lgkmcnt(0)
	v_mfma_f32_16x16x32_bf16 v[118:121], v[208:211], v[170:173], v[118:121]
	v_mfma_f32_16x16x32_bf16 v[114:117], v[216:219], v[170:173], v[114:117]
	v_mfma_f32_16x16x32_bf16 v[102:105], v[208:211], v[178:181], v[102:105]
	v_mfma_f32_16x16x32_bf16 v[98:101], v[216:219], v[178:181], v[98:101]
	v_mfma_f32_16x16x32_bf16 v[86:89], v[208:211], v[186:189], v[86:89]
	v_mfma_f32_16x16x32_bf16 v[82:85], v[216:219], v[186:189], v[82:85]
	v_mfma_f32_16x16x32_bf16 v[70:73], v[208:211], v[194:197], v[70:73]
	v_mfma_f32_16x16x32_bf16 v[66:69], v[216:219], v[194:197], v[66:69]
	v_mfma_f32_16x16x32_bf16 v[118:121], v[212:215], v[174:177], v[118:121]
	v_mfma_f32_16x16x32_bf16 v[114:117], v[220:223], v[174:177], v[114:117]
	v_mfma_f32_16x16x32_bf16 v[102:105], v[212:215], v[182:185], v[102:105]
	v_mfma_f32_16x16x32_bf16 v[98:101], v[220:223], v[182:185], v[98:101]
	v_mfma_f32_16x16x32_bf16 v[86:89], v[212:215], v[190:193], v[86:89]
	v_mfma_f32_16x16x32_bf16 v[82:85], v[220:223], v[190:193], v[82:85]
	v_mfma_f32_16x16x32_bf16 v[70:73], v[212:215], v[198:201], v[70:73]
	v_mfma_f32_16x16x32_bf16 v[66:69], v[220:223], v[198:201], v[66:69]
	s_barrier
	ds_read_b128 v[170:173], v151 offset:16384
	ds_read_b128 v[174:177], v151 offset:17408
	ds_read_b128 v[178:181], v151 offset:18432
	ds_read_b128 v[182:185], v151 offset:19456
	ds_read_b128 v[186:189], v151 offset:20480
	ds_read_b128 v[190:193], v151 offset:21504
	ds_read_b128 v[194:197], v151 offset:22528
	s_mov_b32 m0, s55
	s_add_u32 s100, s60, s22
	s_addc_u32 s101, s61, s23
	ds_read_b128 v[198:201], v151 offset:23552
	global_load_lds_dwordx4 v134, s[60:61]
	s_mov_b32 m0, s72
	s_waitcnt vmcnt(9)
	global_load_lds_dwordx4 v132, s[60:61]
	s_barrier
	s_waitcnt lgkmcnt(0)
	v_mfma_f32_16x16x32_bf16 v[62:65], v[154:157], v[170:173], v[62:65]
	v_mfma_f32_16x16x32_bf16 v[58:61], v[162:165], v[170:173], v[58:61]
	v_mfma_f32_16x16x32_bf16 v[54:57], v[154:157], v[178:181], v[54:57]
	v_mfma_f32_16x16x32_bf16 v[46:49], v[162:165], v[178:181], v[46:49]
	v_mfma_f32_16x16x32_bf16 v[38:41], v[154:157], v[186:189], v[38:41]
	v_mfma_f32_16x16x32_bf16 v[30:33], v[162:165], v[186:189], v[30:33]
	v_mfma_f32_16x16x32_bf16 v[22:25], v[154:157], v[194:197], v[22:25]
	v_mfma_f32_16x16x32_bf16 v[14:17], v[162:165], v[194:197], v[14:17]
	v_mfma_f32_16x16x32_bf16 v[62:65], v[158:161], v[174:177], v[62:65]
	v_mfma_f32_16x16x32_bf16 v[58:61], v[166:169], v[174:177], v[58:61]
	v_mfma_f32_16x16x32_bf16 v[54:57], v[158:161], v[182:185], v[54:57]
	v_mfma_f32_16x16x32_bf16 v[46:49], v[166:169], v[182:185], v[46:49]
	v_mfma_f32_16x16x32_bf16 v[38:41], v[158:161], v[190:193], v[38:41]
	v_mfma_f32_16x16x32_bf16 v[30:33], v[166:169], v[190:193], v[30:33]
	v_mfma_f32_16x16x32_bf16 v[22:25], v[158:161], v[198:201], v[22:25]
	v_mfma_f32_16x16x32_bf16 v[14:17], v[166:169], v[198:201], v[14:17]
	s_barrier
	ds_read_b128 v[154:157], v202 offset:32768
	ds_read_b128 v[158:161], v202 offset:33792
	ds_read_b128 v[162:165], v202 offset:34816
	ds_read_b128 v[166:169], v202 offset:35840
	s_add_i32 s88, s88, s69
	s_mov_b32 m0, s88
	s_add_u32 s86, s58, 0x80000
	s_addc_u32 s87, s59, 0
	global_load_lds_dwordx4 v0, s[86:87]
	s_add_i32 m0, s88, 0x2000
	s_waitcnt vmcnt(5)
	global_load_lds_dwordx4 v130, s[86:87]
	s_barrier
	v_mfma_f32_16x16x32_bf16 v[50:53], v[208:211], v[170:173], v[50:53]
	v_mfma_f32_16x16x32_bf16 v[42:45], v[216:219], v[170:173], v[42:45]
	v_mfma_f32_16x16x32_bf16 v[34:37], v[208:211], v[178:181], v[34:37]
	v_mfma_f32_16x16x32_bf16 v[26:29], v[216:219], v[178:181], v[26:29]
	v_mfma_f32_16x16x32_bf16 v[18:21], v[208:211], v[186:189], v[18:21]
	v_mfma_f32_16x16x32_bf16 v[10:13], v[216:219], v[186:189], v[10:13]
	v_mfma_f32_16x16x32_bf16 v[6:9], v[208:211], v[194:197], v[6:9]
	v_mfma_f32_16x16x32_bf16 v[2:5], v[216:219], v[194:197], v[2:5]
	v_mfma_f32_16x16x32_bf16 v[50:53], v[212:215], v[174:177], v[50:53]
	v_mfma_f32_16x16x32_bf16 v[42:45], v[220:223], v[174:177], v[42:45]
	v_mfma_f32_16x16x32_bf16 v[34:37], v[212:215], v[182:185], v[34:37]
	v_mfma_f32_16x16x32_bf16 v[26:29], v[220:223], v[182:185], v[26:29]
	v_mfma_f32_16x16x32_bf16 v[18:21], v[212:215], v[190:193], v[18:21]
	v_mfma_f32_16x16x32_bf16 v[10:13], v[220:223], v[190:193], v[10:13]
	v_mfma_f32_16x16x32_bf16 v[6:9], v[212:215], v[198:201], v[6:9]
	v_mfma_f32_16x16x32_bf16 v[2:5], v[220:223], v[198:201], v[2:5]
	s_barrier
	s_add_u32 s60, s60, 0x80000
	s_addc_u32 s61, s61, 0
	s_mov_b32 m0, s73
	ds_read_b128 v[170:173], v151 offset:32768
	ds_read_b128 v[174:177], v151 offset:33792
	ds_read_b128 v[178:181], v151 offset:34816
	ds_read_b128 v[182:185], v151 offset:35840
	ds_read_b128 v[186:189], v151 offset:36864
	ds_read_b128 v[190:193], v151 offset:37888
	ds_read_b128 v[194:197], v151 offset:38912
	s_add_i32 s86, 0, 0x18000
	ds_read_b128 v[198:201], v151 offset:39936
	global_load_lds_dwordx4 v134, s[60:61]
	s_mov_b32 m0, s74
	s_waitcnt lgkmcnt(8)
	global_load_lds_dwordx4 v132, s[60:61]
	s_barrier
; #define PG8_STAGE(bufoff, gbase, voff) do { _Pragma("unroll") for (int _i = 0; _i < 2; ++_i) \
;         __builtin_amdgcn_global_load_lds((const unsigned*)((const char*)(gbase) + (voff)[_i]), (LAS unsigned*)(lds + (bufoff) + ldsw + _i * 8192), 16, 0, 0); } while (0)
; #define PG8_LDA(dst, b, h) do { _Pragma("unroll") for (int m = 0; m < 4; ++m) _Pragma("unroll") for (int k = 0; k < 2; ++k) dst[m][k] = *(const LAS bf16x8*)(lds + PG8_SA(b, h) + aoff + m * 2048 + k * 1024); } while (0)
; #define PG8_LDB(dst, b, h) do { _Pragma("unroll") for (int n = 0; n < 2; ++n) _Pragma("unroll") for (int k = 0; k < 2; ++k) dst[n][k] = *(const LAS bf16x8*)(lds + PG8_SB(b, h) + boff + n * 2048 + k * 1024); } while (0)
; #define PG8_MMA(ai, bj, At, Bt) do { __builtin_amdgcn_s_setprio(1); _Pragma("unroll") for (int m = 0; m < 4; ++m) _Pragma("unroll") for (int n = 0; n < 2; ++n) _Pragma("unroll") for (int k = 0; k < 2; ++k) \
;         acc[ai][bj][m][n] = __builtin_amdgcn_mfma_f32_16x16x32_bf16(Bt[n][k], At[m][k], acc[ai][bj][m][n], 0, 0, 0); __builtin_amdgcn_s_setprio(0); } while (0)
; #define PG8_WAIT_V(n) asm volatile("s_waitcnt vmcnt(" #n ")" ::: "memory")
; #define PG8_WAIT_L(n) asm volatile("s_waitcnt lgkmcnt(" #n ")" ::: "memory")
; #define PG8_BAR __builtin_amdgcn_s_barrier()
; #define PG8_SCHED __builtin_amdgcn_sched_barrier(0)
; template <class Epi>
; __device__ __forceinline__ void gemm_phase(LAS unsigned char* lds, const Gemm g, const StaticOrder& S, const Epi& E) {
;     ...
;             PG8_LDB(B1, 1, 1); PG8_STAGE(PG8_SB(1, 0), b3, voffB);
;             PG8_BAR; PG8_WAIT_L(0); PG8_MMA(0, 1, At, B1); PG8_BAR;
;             PG8_LDA(At, 1, 1); PG8_STAGE(PG8_SA(1, 0), a3, voffA);
;             PG8_BAR; PG8_WAIT_L(0); PG8_MMA(1, 0, At, B0); PG8_BAR; PG8_SCHED;
;             PG8_STAGE(PG8_SB(1, 1), b3 + hstep, voffB);
;             PG8_WAIT_V(6); PG8_BAR; PG8_MMA(1, 1, At, B1); PG8_BAR;
	s_waitcnt lgkmcnt(0)
	v_mfma_f32_16x16x32_bf16 v[126:129], v[154:157], v[170:173], v[126:129]
	v_mfma_f32_16x16x32_bf16 v[122:125], v[162:165], v[170:173], v[122:125]
	v_mfma_f32_16x16x32_bf16 v[110:113], v[154:157], v[178:181], v[110:113]
	v_mfma_f32_16x16x32_bf16 v[106:109], v[162:165], v[178:181], v[106:109]
	v_mfma_f32_16x16x32_bf16 v[94:97], v[154:157], v[186:189], v[94:97]
	v_mfma_f32_16x16x32_bf16 v[90:93], v[162:165], v[186:189], v[90:93]
	v_mfma_f32_16x16x32_bf16 v[78:81], v[154:157], v[194:197], v[78:81]
	v_mfma_f32_16x16x32_bf16 v[74:77], v[162:165], v[194:197], v[74:77]
	v_mfma_f32_16x16x32_bf16 v[126:129], v[158:161], v[174:177], v[126:129]
	v_mfma_f32_16x16x32_bf16 v[122:125], v[166:169], v[174:177], v[122:125]
	v_mfma_f32_16x16x32_bf16 v[110:113], v[158:161], v[182:185], v[110:113]
	v_mfma_f32_16x16x32_bf16 v[106:109], v[166:169], v[182:185], v[106:109]
	v_mfma_f32_16x16x32_bf16 v[94:97], v[158:161], v[190:193], v[94:97]
	v_mfma_f32_16x16x32_bf16 v[90:93], v[166:169], v[190:193], v[90:93]
	v_mfma_f32_16x16x32_bf16 v[78:81], v[158:161], v[198:201], v[78:81]
	v_mfma_f32_16x16x32_bf16 v[74:77], v[166:169], v[198:201], v[74:77]
	s_barrier
	s_add_i32 s61, s86, s69
	s_mov_b32 m0, s61
	ds_read_b128 v[208:211], v202 offset:49152
	ds_read_b128 v[212:215], v202 offset:50176
	ds_read_b128 v[216:219], v202 offset:51200
	ds_read_b128 v[220:223], v202 offset:52224
	global_load_lds_dwordx4 v0, s[98:99]
	s_add_i32 m0, s61, 0x2000
	s_add_i32 s60, 0, 0x1c000
	global_load_lds_dwordx4 v130, s[98:99]
	s_barrier
	s_waitcnt lgkmcnt(0)
	v_mfma_f32_16x16x32_bf16 v[118:121], v[208:211], v[170:173], v[118:121]
	v_mfma_f32_16x16x32_bf16 v[114:117], v[216:219], v[170:173], v[114:117]
	v_mfma_f32_16x16x32_bf16 v[102:105], v[208:211], v[178:181], v[102:105]
	v_mfma_f32_16x16x32_bf16 v[98:101], v[216:219], v[178:181], v[98:101]
	v_mfma_f32_16x16x32_bf16 v[86:89], v[208:211], v[186:189], v[86:89]
	v_mfma_f32_16x16x32_bf16 v[82:85], v[216:219], v[186:189], v[82:85]
	v_mfma_f32_16x16x32_bf16 v[70:73], v[208:211], v[194:197], v[70:73]
	v_mfma_f32_16x16x32_bf16 v[66:69], v[216:219], v[194:197], v[66:69]
	v_mfma_f32_16x16x32_bf16 v[118:121], v[212:215], v[174:177], v[118:121]
	v_mfma_f32_16x16x32_bf16 v[114:117], v[220:223], v[174:177], v[114:117]
	v_mfma_f32_16x16x32_bf16 v[102:105], v[212:215], v[182:185], v[102:105]
	v_mfma_f32_16x16x32_bf16 v[98:101], v[220:223], v[182:185], v[98:101]
	v_mfma_f32_16x16x32_bf16 v[86:89], v[212:215], v[190:193], v[86:89]
	v_mfma_f32_16x16x32_bf16 v[82:85], v[220:223], v[190:193], v[82:85]
	v_mfma_f32_16x16x32_bf16 v[70:73], v[212:215], v[198:201], v[70:73]
	v_mfma_f32_16x16x32_bf16 v[66:69], v[220:223], v[198:201], v[66:69]
	s_barrier
	ds_read_b128 v[170:173], v151 offset:49152
	ds_read_b128 v[174:177], v151 offset:50176
	ds_read_b128 v[178:181], v151 offset:51200
	ds_read_b128 v[182:185], v151 offset:52224
	ds_read_b128 v[186:189], v151 offset:53248
	ds_read_b128 v[190:193], v151 offset:54272
	ds_read_b128 v[194:197], v151 offset:55296
	s_mov_b32 m0, s76
	ds_read_b128 v[198:201], v151 offset:56320
	global_load_lds_dwordx4 v134, s[100:101]
	s_mov_b32 m0, s77
	s_waitcnt vmcnt(9)
	global_load_lds_dwordx4 v132, s[100:101]
	s_barrier
	s_waitcnt lgkmcnt(0)
	v_mfma_f32_16x16x32_bf16 v[62:65], v[154:157], v[170:173], v[62:65]
	v_mfma_f32_16x16x32_bf16 v[58:61], v[162:165], v[170:173], v[58:61]
	v_mfma_f32_16x16x32_bf16 v[54:57], v[154:157], v[178:181], v[54:57]
	v_mfma_f32_16x16x32_bf16 v[46:49], v[162:165], v[178:181], v[46:49]
	v_mfma_f32_16x16x32_bf16 v[38:41], v[154:157], v[186:189], v[38:41]
	v_mfma_f32_16x16x32_bf16 v[30:33], v[162:165], v[186:189], v[30:33]
	v_mfma_f32_16x16x32_bf16 v[22:25], v[154:157], v[194:197], v[22:25]
	v_mfma_f32_16x16x32_bf16 v[14:17], v[162:165], v[194:197], v[14:17]
	v_mfma_f32_16x16x32_bf16 v[62:65], v[158:161], v[174:177], v[62:65]
	v_mfma_f32_16x16x32_bf16 v[58:61], v[166:169], v[174:177], v[58:61]
	v_mfma_f32_16x16x32_bf16 v[54:57], v[158:161], v[182:185], v[54:57]
	v_mfma_f32_16x16x32_bf16 v[46:49], v[166:169], v[182:185], v[46:49]
	v_mfma_f32_16x16x32_bf16 v[38:41], v[158:161], v[190:193], v[38:41]
	v_mfma_f32_16x16x32_bf16 v[30:33], v[166:169], v[190:193], v[30:33]
	v_mfma_f32_16x16x32_bf16 v[22:25], v[158:161], v[198:201], v[22:25]
	v_mfma_f32_16x16x32_bf16 v[14:17], v[166:169], v[198:201], v[14:17]
	s_barrier
	ds_read_b128 v[154:157], v202
	ds_read_b128 v[158:161], v202 offset:1024
	ds_read_b128 v[162:165], v202 offset:2048
	s_add_i32 s85, s85, 2
	s_add_u32 s56, s56, 0x100
	s_addc_u32 s57, s57, 0
	s_add_u32 s83, s83, 0x100
	s_addc_u32 s84, s84, 0
	ds_read_b128 v[166:169], v202 offset:3072
	s_add_i32 s60, s60, s69
	s_mov_b32 m0, s60
	s_add_u32 s58, s58, 0x80080
	s_addc_u32 s59, s59, 0
	global_load_lds_dwordx4 v0, s[58:59]
	s_add_i32 m0, s60, 0x2000
	s_waitcnt vmcnt(5)
	global_load_lds_dwordx4 v130, s[58:59]
	s_barrier
	v_mfma_f32_16x16x32_bf16 v[50:53], v[208:211], v[170:173], v[50:53]
	v_mfma_f32_16x16x32_bf16 v[42:45], v[216:219], v[170:173], v[42:45]
	v_mfma_f32_16x16x32_bf16 v[34:37], v[208:211], v[178:181], v[34:37]
	v_mfma_f32_16x16x32_bf16 v[26:29], v[216:219], v[178:181], v[26:29]
	v_mfma_f32_16x16x32_bf16 v[18:21], v[208:211], v[186:189], v[18:21]
	v_mfma_f32_16x16x32_bf16 v[10:13], v[216:219], v[186:189], v[10:13]
	v_mfma_f32_16x16x32_bf16 v[6:9], v[208:211], v[194:197], v[6:9]
	v_mfma_f32_16x16x32_bf16 v[2:5], v[216:219], v[194:197], v[2:5]
	v_mfma_f32_16x16x32_bf16 v[50:53], v[212:215], v[174:177], v[50:53]
	v_mfma_f32_16x16x32_bf16 v[42:45], v[220:223], v[174:177], v[42:45]
	v_mfma_f32_16x16x32_bf16 v[34:37], v[212:215], v[182:185], v[34:37]
	v_mfma_f32_16x16x32_bf16 v[26:29], v[220:223], v[182:185], v[26:29]
	v_mfma_f32_16x16x32_bf16 v[18:21], v[212:215], v[190:193], v[18:21]
	v_mfma_f32_16x16x32_bf16 v[10:13], v[220:223], v[190:193], v[10:13]
	v_mfma_f32_16x16x32_bf16 v[6:9], v[212:215], v[198:201], v[6:9]
	v_mfma_f32_16x16x32_bf16 v[2:5], v[220:223], v[198:201], v[2:5]
	s_cmp_gt_u32 s85, 29
	s_barrier
; __device__ __forceinline__ unsigned pk2(float lo, float hi) { f32x2 v = {lo, hi}; bf16x2_t b = __builtin_convertvector(v, bf16x2_t); return __builtin_bit_cast(unsigned, b); }
;     __device__ __forceinline__ void operator()(const AccT& acc, const Unit& u, int wr, int wc, int fr, int fq) const {
;     ...
;         if (ss) {
;             const int ln = (fq << 4) | fr;
;             float sa = ss[u.pm * BM + wr * 64 + ln], sb = ss[u.pm * BM + HALF + wr * 64 + ln];
;             sa = __builtin_amdgcn_rsqf(sa * (1.0f / DM) + EPS); sb = __builtin_amdgcn_rsqf(sb * (1.0f / DM) + EPS);
; #pragma unroll
;             for (int m = 0; m < 4; ++m) { rsv[m] = __shfl(sa, 16 * m + fr); rsv[4 + m] = __shfl(sb, 16 * m + fr); }
;         } else {
; #pragma unroll
;             for (int i = 0; i < 8; ++i) rsv[i] = 1.0f;
;         }
; #pragma unroll
;         for (int ai = 0; ai < 2; ++ai)
; #pragma unroll
;             for (int m = 0; m < 4; ++m) {
;                 const int row = row0 + ai * HALF + m * 16;
;                 const float rs = rsv[ai * 4 + m];
; #pragma unroll
;                 for (int bj = 0; bj < 2; ++bj) {
;                     const f32x4 v0 = acc[ai][bj][m][0] * rs, v1 = acc[ai][bj][m][1] * rs;
;                     u32x4 w; w.x = pk2(v0[0], v0[1]); w.y = pk2(v0[2], v0[3]); w.z = pk2(v1[0], v1[1]); w.w = pk2(v1[2], v1[3]);
;                     *(u32x4*)(out + (size_t)row * ldo + col0 + bj * HALF) = w;
	s_cbranch_scc0 .LBB0_64
	s_waitcnt lgkmcnt(0)
	s_lshl_b32 s47, s54, 8
	s_add_i32 s47, s47, s75
	v_lshl_or_b32 v158, s80, 8, v149
	v_ashrrev_i32_e32 v159, 31, v158
	s_and_b64 vcc, exec, s[36:37]
	s_mov_b32 s80, s46
	s_mov_b32 s54, s48
	s_mov_b64 s[58:59], s[52:53]
	v_fmamk_f32 v140, v140, 0x3a000000, v233
	v_rsq_f32_e32 v140, v140
	v_fmamk_f32 v142, v142, 0x3a000000, v233
	ds_bpermute_b32 v154, v152, v140
	v_rsq_f32_e32 v153, v142
	ds_bpermute_b32 v156, v152, v140 offset:64
	ds_bpermute_b32 v150, v152, v140 offset:128
	ds_bpermute_b32 v148, v152, v140 offset:192
	ds_bpermute_b32 v146, v152, v153
	ds_bpermute_b32 v144, v152, v153 offset:64
	ds_bpermute_b32 v142, v152, v153 offset:128
	ds_bpermute_b32 v140, v152, v153 offset:192
	v_or_b32_e32 v153, s47, v141
	s_waitcnt lgkmcnt(0)
	v_pk_mul_f32 v[126:127], v[126:127], v[154:155] op_sel_hi:[1,0]
	v_pk_mul_f32 v[122:123], v[122:123], v[154:155] op_sel_hi:[1,0]
	v_pk_mul_f32 v[128:129], v[128:129], v[154:155] op_sel_hi:[1,0]
	v_pk_mul_f32 v[160:161], v[124:125], v[154:155] op_sel_hi:[1,0]
	v_cvt_pk_bf16_f32 v124, v126, v127
	v_cvt_pk_bf16_f32 v126, v122, v123
	v_mad_i64_i32 v[122:123], s[56:57], v153, s63, 0
	v_cvt_pk_bf16_f32 v125, v128, v129
	v_lshl_add_u64 v[128:129], v[122:123], 1, s[44:45]
	v_lshlrev_b64 v[122:123], 1, v[158:159]
	v_cvt_pk_bf16_f32 v127, v160, v161
	v_lshl_add_u64 v[128:129], v[128:129], 0, v[122:123]
	global_store_dwordx4 v[128:129], v[124:127], off
	v_pk_mul_f32 v[120:121], v[120:121], v[154:155] op_sel_hi:[1,0]
	v_pk_mul_f32 v[118:119], v[118:119], v[154:155] op_sel_hi:[1,0]
	v_pk_mul_f32 v[124:125], v[116:117], v[154:155] op_sel_hi:[1,0]
	v_pk_mul_f32 v[116:117], v[114:115], v[154:155] op_sel_hi:[1,0]
	v_cvt_pk_bf16_f32 v114, v118, v119
	v_cvt_pk_bf16_f32 v115, v120, v121
	v_cvt_pk_bf16_f32 v116, v116, v117
	v_cvt_pk_bf16_f32 v117, v124, v125
	global_store_dwordx4 v[128:129], v[114:117], off offset:256
	v_pk_mul_f32 v[110:111], v[110:111], v[156:157] op_sel_hi:[1,0]
	v_pk_mul_f32 v[112:113], v[112:113], v[156:157] op_sel_hi:[1,0]
	v_or_b32_e32 v116, 16, v153
	v_pk_mul_f32 v[114:115], v[108:109], v[156:157] op_sel_hi:[1,0]
	v_pk_mul_f32 v[108:109], v[106:107], v[156:157] op_sel_hi:[1,0]
	v_cvt_pk_bf16_f32 v106, v110, v111
	v_mad_i64_i32 v[110:111], s[56:57], v116, s63, 0
	v_lshl_add_u64 v[110:111], v[110:111], 1, s[44:45]
	v_cvt_pk_bf16_f32 v107, v112, v113
	v_cvt_pk_bf16_f32 v108, v108, v109
	v_cvt_pk_bf16_f32 v109, v114, v115
	v_lshl_add_u64 v[110:111], v[110:111], 0, v[122:123]
	global_store_dwordx4 v[110:111], v[106:109], off
	v_pk_mul_f32 v[104:105], v[104:105], v[156:157] op_sel_hi:[1,0]
	v_pk_mul_f32 v[102:103], v[102:103], v[156:157] op_sel_hi:[1,0]
	v_pk_mul_f32 v[106:107], v[100:101], v[156:157] op_sel_hi:[1,0]
	v_pk_mul_f32 v[100:101], v[98:99], v[156:157] op_sel_hi:[1,0]
	v_cvt_pk_bf16_f32 v98, v102, v103
	v_cvt_pk_bf16_f32 v99, v104, v105
	v_cvt_pk_bf16_f32 v100, v100, v101
	v_cvt_pk_bf16_f32 v101, v106, v107
	global_store_dwordx4 v[110:111], v[98:101], off offset:256
	v_pk_mul_f32 v[94:95], v[94:95], v[150:151] op_sel_hi:[1,0]
	v_pk_mul_f32 v[96:97], v[96:97], v[150:151] op_sel_hi:[1,0]
	v_or_b32_e32 v100, 32, v153
	v_pk_mul_f32 v[98:99], v[92:93], v[150:151] op_sel_hi:[1,0]
	v_pk_mul_f32 v[92:93], v[90:91], v[150:151] op_sel_hi:[1,0]
	v_cvt_pk_bf16_f32 v90, v94, v95
	v_mad_i64_i32 v[94:95], s[56:57], v100, s63, 0
	v_lshl_add_u64 v[94:95], v[94:95], 1, s[44:45]
	v_cvt_pk_bf16_f32 v91, v96, v97
	v_cvt_pk_bf16_f32 v92, v92, v93
	v_cvt_pk_bf16_f32 v93, v98, v99
	v_lshl_add_u64 v[94:95], v[94:95], 0, v[122:123]
	global_store_dwordx4 v[94:95], v[90:93], off
	v_pk_mul_f32 v[88:89], v[88:89], v[150:151] op_sel_hi:[1,0]
	v_pk_mul_f32 v[86:87], v[86:87], v[150:151] op_sel_hi:[1,0]
	v_pk_mul_f32 v[90:91], v[84:85], v[150:151] op_sel_hi:[1,0]
	v_pk_mul_f32 v[84:85], v[82:83], v[150:151] op_sel_hi:[1,0]
	v_cvt_pk_bf16_f32 v82, v86, v87
	v_cvt_pk_bf16_f32 v83, v88, v89
	v_cvt_pk_bf16_f32 v84, v84, v85
	v_cvt_pk_bf16_f32 v85, v90, v91
	global_store_dwordx4 v[94:95], v[82:85], off offset:256
	v_pk_mul_f32 v[78:79], v[78:79], v[148:149] op_sel_hi:[1,0]
	v_pk_mul_f32 v[80:81], v[80:81], v[148:149] op_sel_hi:[1,0]
	v_or_b32_e32 v84, 48, v153
	v_pk_mul_f32 v[82:83], v[76:77], v[148:149] op_sel_hi:[1,0]
	v_pk_mul_f32 v[76:77], v[74:75], v[148:149] op_sel_hi:[1,0]
	v_cvt_pk_bf16_f32 v74, v78, v79
	v_mad_i64_i32 v[78:79], s[56:57], v84, s63, 0
	v_lshl_add_u64 v[78:79], v[78:79], 1, s[44:45]
	v_cvt_pk_bf16_f32 v75, v80, v81
	v_cvt_pk_bf16_f32 v76, v76, v77
	v_cvt_pk_bf16_f32 v77, v82, v83
	v_lshl_add_u64 v[78:79], v[78:79], 0, v[122:123]
	global_store_dwordx4 v[78:79], v[74:77], off
; __device__ __forceinline__ unsigned pk2(float lo, float hi) { f32x2 v = {lo, hi}; bf16x2_t b = __builtin_convertvector(v, bf16x2_t); return __builtin_bit_cast(unsigned, b); }
; #define PG8_WAIT_V(n) asm volatile("s_waitcnt vmcnt(" #n ")" ::: "memory")
; #define PG8_BAR __builtin_amdgcn_s_barrier()
;     __device__ __forceinline__ void operator()(const AccT& acc, const Unit& u, int wr, int wc, int fr, int fq) const {
;     ...
;             for (int m = 0; m < 4; ++m) {
;                 const int row = row0 + ai * HALF + m * 16;
;                 const float rs = rsv[ai * 4 + m];
; #pragma unroll
;                 for (int bj = 0; bj < 2; ++bj) {
;                     const f32x4 v0 = acc[ai][bj][m][0] * rs, v1 = acc[ai][bj][m][1] * rs;
;                     u32x4 w; w.x = pk2(v0[0], v0[1]); w.y = pk2(v0[2], v0[3]); w.z = pk2(v1[0], v1[1]); w.w = pk2(v1[2], v1[3]);
;                     *(u32x4*)(out + (size_t)row * ldo + col0 + bj * HALF) = w;
;                 }
; template <class Epi>
; __device__ __forceinline__ void gemm_phase(LAS unsigned char* lds, const Gemm g, const StaticOrder& S, const Epi& E) {
;     ...
;         if (!has_next) break;
; #pragma unroll
;         for (int a = 0; a < 2; ++a)
; #pragma unroll
;             for (int b = 0; b < 2; ++b)
; #pragma unroll
;                 for (int m = 0; m < 4; ++m)
; #pragma unroll
;                     for (int n = 0; n < 2; ++n) acc[a][b][m][n] = (f32x4){0.f, 0.f, 0.f, 0.f};
;         cur = nxt; cA = nA; cB = nB; ++ui;
;     }
;     PG8_WAIT_V(0);
;     if (wr == 0) PG8_BAR;
;     PG8_BAR;
	v_pk_mul_f32 v[72:73], v[72:73], v[148:149] op_sel_hi:[1,0]
	v_pk_mul_f32 v[70:71], v[70:71], v[148:149] op_sel_hi:[1,0]
	v_pk_mul_f32 v[74:75], v[68:69], v[148:149] op_sel_hi:[1,0]
	v_pk_mul_f32 v[68:69], v[66:67], v[148:149] op_sel_hi:[1,0]
	v_cvt_pk_bf16_f32 v66, v70, v71
	v_cvt_pk_bf16_f32 v67, v72, v73
	v_cvt_pk_bf16_f32 v68, v68, v69
	v_cvt_pk_bf16_f32 v69, v74, v75
	global_store_dwordx4 v[78:79], v[66:69], off offset:256
	v_pk_mul_f32 v[62:63], v[62:63], v[146:147] op_sel_hi:[1,0]
	v_pk_mul_f32 v[64:65], v[64:65], v[146:147] op_sel_hi:[1,0]
	v_add_u32_e32 v68, 0x80, v153
	v_pk_mul_f32 v[66:67], v[60:61], v[146:147] op_sel_hi:[1,0]
	v_pk_mul_f32 v[60:61], v[58:59], v[146:147] op_sel_hi:[1,0]
	v_cvt_pk_bf16_f32 v58, v62, v63
	v_mad_i64_i32 v[62:63], s[56:57], v68, s63, 0
	v_lshl_add_u64 v[62:63], v[62:63], 1, s[44:45]
	v_cvt_pk_bf16_f32 v59, v64, v65
	v_cvt_pk_bf16_f32 v60, v60, v61
	v_cvt_pk_bf16_f32 v61, v66, v67
	v_lshl_add_u64 v[62:63], v[62:63], 0, v[122:123]
	global_store_dwordx4 v[62:63], v[58:61], off
	v_pk_mul_f32 v[52:53], v[52:53], v[146:147] op_sel_hi:[1,0]
	v_pk_mul_f32 v[50:51], v[50:51], v[146:147] op_sel_hi:[1,0]
	v_pk_mul_f32 v[58:59], v[44:45], v[146:147] op_sel_hi:[1,0]
	v_pk_mul_f32 v[44:45], v[42:43], v[146:147] op_sel_hi:[1,0]
	v_cvt_pk_bf16_f32 v42, v50, v51
	v_cvt_pk_bf16_f32 v43, v52, v53
	v_cvt_pk_bf16_f32 v44, v44, v45
	v_cvt_pk_bf16_f32 v45, v58, v59
	global_store_dwordx4 v[62:63], v[42:45], off offset:256
	v_add_u32_e32 v50, 0x90, v153
	v_pk_mul_f32 v[46:47], v[46:47], v[144:145] op_sel_hi:[1,0]
	v_pk_mul_f32 v[44:45], v[56:57], v[144:145] op_sel_hi:[1,0]
	v_pk_mul_f32 v[42:43], v[54:55], v[144:145] op_sel_hi:[1,0]
	v_pk_mul_f32 v[48:49], v[48:49], v[144:145] op_sel_hi:[1,0]
	v_cvt_pk_bf16_f32 v42, v42, v43
	v_cvt_pk_bf16_f32 v43, v44, v45
	v_cvt_pk_bf16_f32 v44, v46, v47
	v_mad_i64_i32 v[46:47], s[56:57], v50, s63, 0
	v_lshl_add_u64 v[46:47], v[46:47], 1, s[44:45]
	v_cvt_pk_bf16_f32 v45, v48, v49
	v_lshl_add_u64 v[46:47], v[46:47], 0, v[122:123]
	global_store_dwordx4 v[46:47], v[42:45], off
	v_pk_mul_f32 v[36:37], v[36:37], v[144:145] op_sel_hi:[1,0]
	v_pk_mul_f32 v[34:35], v[34:35], v[144:145] op_sel_hi:[1,0]
	v_pk_mul_f32 v[42:43], v[28:29], v[144:145] op_sel_hi:[1,0]
	v_pk_mul_f32 v[28:29], v[26:27], v[144:145] op_sel_hi:[1,0]
	v_cvt_pk_bf16_f32 v26, v34, v35
	v_cvt_pk_bf16_f32 v27, v36, v37
	v_cvt_pk_bf16_f32 v28, v28, v29
	v_cvt_pk_bf16_f32 v29, v42, v43
	global_store_dwordx4 v[46:47], v[26:29], off offset:256
	v_add_u32_e32 v34, 0xa0, v153
	v_pk_mul_f32 v[30:31], v[30:31], v[142:143] op_sel_hi:[1,0]
	v_pk_mul_f32 v[28:29], v[40:41], v[142:143] op_sel_hi:[1,0]
	v_pk_mul_f32 v[26:27], v[38:39], v[142:143] op_sel_hi:[1,0]
	v_pk_mul_f32 v[32:33], v[32:33], v[142:143] op_sel_hi:[1,0]
	v_cvt_pk_bf16_f32 v26, v26, v27
	v_cvt_pk_bf16_f32 v27, v28, v29
	v_cvt_pk_bf16_f32 v28, v30, v31
	v_mad_i64_i32 v[30:31], s[56:57], v34, s63, 0
	v_lshl_add_u64 v[30:31], v[30:31], 1, s[44:45]
	v_cvt_pk_bf16_f32 v29, v32, v33
	v_lshl_add_u64 v[30:31], v[30:31], 0, v[122:123]
	global_store_dwordx4 v[30:31], v[26:29], off
	v_pk_mul_f32 v[20:21], v[20:21], v[142:143] op_sel_hi:[1,0]
	v_pk_mul_f32 v[18:19], v[18:19], v[142:143] op_sel_hi:[1,0]
	v_pk_mul_f32 v[26:27], v[12:13], v[142:143] op_sel_hi:[1,0]
	v_pk_mul_f32 v[12:13], v[10:11], v[142:143] op_sel_hi:[1,0]
	v_cvt_pk_bf16_f32 v10, v18, v19
	v_cvt_pk_bf16_f32 v11, v20, v21
	v_cvt_pk_bf16_f32 v12, v12, v13
	v_cvt_pk_bf16_f32 v13, v26, v27
	global_store_dwordx4 v[30:31], v[10:13], off offset:256
	v_add_u32_e32 v18, 0xb0, v153
	v_pk_mul_f32 v[14:15], v[14:15], v[140:141] op_sel_hi:[1,0]
	v_pk_mul_f32 v[12:13], v[24:25], v[140:141] op_sel_hi:[1,0]
	v_pk_mul_f32 v[10:11], v[22:23], v[140:141] op_sel_hi:[1,0]
	v_pk_mul_f32 v[16:17], v[16:17], v[140:141] op_sel_hi:[1,0]
	v_cvt_pk_bf16_f32 v10, v10, v11
	v_cvt_pk_bf16_f32 v11, v12, v13
	v_cvt_pk_bf16_f32 v12, v14, v15
	v_mad_i64_i32 v[14:15], s[56:57], v18, s63, 0
	v_lshl_add_u64 v[14:15], v[14:15], 1, s[44:45]
	v_cvt_pk_bf16_f32 v13, v16, v17
	v_lshl_add_u64 v[14:15], v[14:15], 0, v[122:123]
	global_store_dwordx4 v[14:15], v[10:13], off
	v_pk_mul_f32 v[8:9], v[8:9], v[140:141] op_sel_hi:[1,0]
	v_pk_mul_f32 v[6:7], v[6:7], v[140:141] op_sel_hi:[1,0]
	v_pk_mul_f32 v[10:11], v[4:5], v[140:141] op_sel_hi:[1,0]
	v_pk_mul_f32 v[4:5], v[2:3], v[140:141] op_sel_hi:[1,0]
	v_cvt_pk_bf16_f32 v2, v6, v7
	v_cvt_pk_bf16_f32 v3, v8, v9
	v_cvt_pk_bf16_f32 v4, v4, v5
	v_cvt_pk_bf16_f32 v5, v10, v11
	s_mov_b64 s[56:57], s[50:51]
	global_store_dwordx4 v[14:15], v[2:5], off offset:256
	s_cbranch_vccz .LBB0_61
	s_waitcnt vmcnt(0)
	s_cmpk_gt_u32 s64, 0xff
	s_cbranch_scc1 .LBB0_68
	s_barrier

; #define PG8_BAR __builtin_amdgcn_s_barrier()
; template <class Epi>
; __device__ __forceinline__ void gemm_phase(LAS unsigned char* lds, const Gemm g, const StaticOrder& S, const Epi& E) {
;     ...
;     for (;;) {
;         const bool has_next = S.next(ui + 1, nxt);
;         const char* nA = has_next ? (const char*)g.A + (size_t)nxt.pm * tstep : cA; const char* nB = has_next ? (const char*)g.Bt + (size_t)nxt.pn * tstep : cB;
;         for (int t = 0; t < nt; t += 2) {
;             const bool last = (t == nt - 2);
;             const char* a1 = cA + (size_t)(t + 1) * kstep;
;             const char* a2 = last ? nA : cA + (size_t)(t + 2) * kstep; const char* b2 = last ? nB : cB + (size_t)(t + 2) * kstep;
;             const char* a3 = a2 + kstep; const char* b3 = b2 + kstep;
;             PG8_LDB(B0, 0, 0); PG8_SCHED; PG8_LDA(At, 0, 0); PG8_STAGE(PG8_SA(1, 1), a1 + hstep, voffA);
;             PG8_WAIT_L(8); PG8_BAR; PG8_WAIT_L(0); PG8_MMA(0, 0, At, B0); PG8_BAR; PG8_SCHED;
;             PG8_LDB(B1, 0, 1); PG8_STAGE(PG8_SB(0, 0), b2, voffB);
;             PG8_BAR; PG8_WAIT_L(0); PG8_MMA(0, 1, At, B1); PG8_BAR;
;             PG8_LDA(At, 0, 1); PG8_STAGE(PG8_SA(0, 0), a2, voffA);
;             PG8_BAR; PG8_WAIT_L(0); PG8_MMA(1, 0, At, B0); PG8_BAR; PG8_SCHED;
;             PG8_STAGE(PG8_SB(0, 1), b2 + hstep, voffB);
;             PG8_WAIT_V(6); PG8_BAR; PG8_MMA(1, 1, At, B1); PG8_BAR;
;             PG8_LDB(B0, 1, 0); PG8_SCHED; PG8_LDA(At, 1, 0); PG8_STAGE(PG8_SA(0, 1), a2 + hstep, voffA);
;             PG8_WAIT_L(8); PG8_BAR; PG8_WAIT_L(0); PG8_MMA(0, 0, At, B0); PG8_BAR; PG8_SCHED;
;             PG8_LDB(B1, 1, 1); PG8_STAGE(PG8_SB(1, 0), b3, voffB);
;             PG8_BAR; PG8_WAIT_L(0); PG8_MMA(0, 1, At, B1); PG8_BAR;
;             PG8_LDA(At, 1, 1); PG8_STAGE(PG8_SA(1, 0), a3, voffA);
;             PG8_BAR; PG8_WAIT_L(0); PG8_MMA(1, 0, At, B0); PG8_BAR; PG8_SCHED;
;             PG8_STAGE(PG8_SB(1, 1), b3 + hstep, voffB);
;             PG8_WAIT_V(6); PG8_BAR; PG8_MMA(1, 1, At, B1); PG8_BAR;
;         }
;         E(acc, cur, wr, wc, fr, fq);
;         if (!has_next) break;
; #pragma unroll
;         for (int a = 0; a < 2; ++a)
; #pragma unroll
;             for (int b = 0; b < 2; ++b)
; #pragma unroll
;                 for (int m = 0; m < 4; ++m)
; #pragma unroll
;                     for (int n = 0; n < 2; ++n) acc[a][b][m][n] = (f32x4){0.f, 0.f, 0.f, 0.f};
.LBB0_89:
	v_mov_b64_e32 v[2:3], 0x580
	s_ashr_i32 s41, s40, 31
	v_cmp_lt_i64_e32 vcc, s[42:43], v[2:3]
	s_lshl_b64 s[42:43], s[40:41], 20
	v_readlane_b32 s44, v254, 8
	v_readlane_b32 s45, v254, 9
	s_add_u32 s42, s44, s42
	s_addc_u32 s43, s45, s43
	s_and_b64 s[44:45], vcc, exec
	s_cselect_b32 s41, s43, s47
	s_cselect_b32 s69, s42, s46
	s_ashr_i32 s39, s38, 31
	s_lshl_b64 s[44:45], s[38:39], 20
	s_add_u32 s44, s53, s44
	s_addc_u32 s45, s54, s45
	s_and_b64 s[50:51], vcc, exec
	s_cselect_b32 s39, s45, s49
	s_cselect_b32 s70, s44, s48
	s_add_u32 s46, s46, 0x80080
	s_addc_u32 s47, s47, 0
	s_add_u32 s71, s48, 0x100
	v_mov_b32_e32 v2, 0
	s_addc_u32 s72, s49, 0
	s_mov_b32 s73, -2
	v_mov_b32_e32 v3, v2
	v_mov_b32_e32 v4, v2
	v_mov_b32_e32 v5, v2
	v_mov_b32_e32 v10, v2
	v_mov_b32_e32 v11, v2
	v_mov_b32_e32 v12, v2
	v_mov_b32_e32 v13, v2
	v_mov_b32_e32 v18, v2
	v_mov_b32_e32 v19, v2
	v_mov_b32_e32 v20, v2
	v_mov_b32_e32 v21, v2
	s_waitcnt vmcnt(0)
	v_mov_b32_e32 v26, v2
	v_mov_b32_e32 v27, v2
	v_mov_b32_e32 v28, v2
	v_mov_b32_e32 v29, v2
	v_mov_b32_e32 v34, v2
	v_mov_b32_e32 v35, v2
	v_mov_b32_e32 v36, v2
	v_mov_b32_e32 v37, v2
	v_mov_b32_e32 v42, v2
	v_mov_b32_e32 v43, v2
	v_mov_b32_e32 v44, v2
	v_mov_b32_e32 v45, v2
	v_mov_b32_e32 v50, v2
	v_mov_b32_e32 v51, v2
	v_mov_b32_e32 v52, v2
	v_mov_b32_e32 v53, v2
	v_mov_b32_e32 v58, v2
	v_mov_b32_e32 v59, v2
	v_mov_b32_e32 v60, v2
	v_mov_b32_e32 v61, v2
	v_mov_b32_e32 v6, v2
	v_mov_b32_e32 v7, v2
	v_mov_b32_e32 v8, v2
	v_mov_b32_e32 v9, v2
	v_mov_b32_e32 v14, v2
	v_mov_b32_e32 v15, v2
	v_mov_b32_e32 v16, v2
	v_mov_b32_e32 v17, v2
	v_mov_b32_e32 v22, v2
	v_mov_b32_e32 v23, v2
	v_mov_b32_e32 v24, v2
	v_mov_b32_e32 v25, v2
	v_mov_b32_e32 v30, v2
	v_mov_b32_e32 v31, v2
	v_mov_b32_e32 v32, v2
	v_mov_b32_e32 v33, v2
	v_mov_b32_e32 v38, v2
	v_mov_b32_e32 v39, v2
	v_mov_b32_e32 v40, v2
	v_mov_b32_e32 v41, v2
	v_mov_b32_e32 v46, v2
	v_mov_b32_e32 v47, v2
	v_mov_b32_e32 v48, v2
	v_mov_b32_e32 v49, v2
	v_mov_b32_e32 v54, v2
	v_mov_b32_e32 v55, v2
	v_mov_b32_e32 v56, v2
	v_mov_b32_e32 v57, v2
	v_mov_b32_e32 v62, v2
	v_mov_b32_e32 v63, v2
	v_mov_b32_e32 v64, v2
	v_mov_b32_e32 v65, v2
	v_mov_b32_e32 v66, v2
	v_mov_b32_e32 v67, v2
	v_mov_b32_e32 v68, v2
	v_mov_b32_e32 v69, v2
	v_mov_b32_e32 v74, v2
	v_mov_b32_e32 v75, v2
	v_mov_b32_e32 v76, v2
	v_mov_b32_e32 v77, v2
	v_mov_b32_e32 v82, v2
	v_mov_b32_e32 v83, v2
	v_mov_b32_e32 v84, v2
	v_mov_b32_e32 v85, v2
	v_mov_b32_e32 v90, v2
	v_mov_b32_e32 v91, v2
	v_mov_b32_e32 v92, v2
	v_mov_b32_e32 v93, v2
	v_mov_b32_e32 v98, v2
	v_mov_b32_e32 v99, v2
	v_mov_b32_e32 v100, v2
	v_mov_b32_e32 v101, v2
	v_mov_b32_e32 v106, v2
	v_mov_b32_e32 v107, v2
	v_mov_b32_e32 v108, v2
	v_mov_b32_e32 v109, v2
	v_mov_b32_e32 v114, v2
	v_mov_b32_e32 v115, v2
	v_mov_b32_e32 v116, v2
	v_mov_b32_e32 v117, v2
	v_mov_b32_e32 v118, v2
	v_mov_b32_e32 v119, v2
	v_mov_b32_e32 v120, v2
	v_mov_b32_e32 v121, v2
	v_mov_b32_e32 v70, v2
	v_mov_b32_e32 v71, v2
	v_mov_b32_e32 v72, v2
	v_mov_b32_e32 v73, v2
	v_mov_b32_e32 v78, v2
	v_mov_b32_e32 v79, v2
	v_mov_b32_e32 v80, v2
	v_mov_b32_e32 v81, v2
	v_mov_b32_e32 v86, v2
	v_mov_b32_e32 v87, v2
	v_mov_b32_e32 v88, v2
	v_mov_b32_e32 v89, v2
	v_mov_b32_e32 v94, v2
	v_mov_b32_e32 v95, v2
	v_mov_b32_e32 v96, v2
	v_mov_b32_e32 v97, v2
	v_mov_b32_e32 v102, v2
	v_mov_b32_e32 v103, v2
	v_mov_b32_e32 v104, v2
	v_mov_b32_e32 v105, v2
	v_mov_b32_e32 v110, v2
	v_mov_b32_e32 v111, v2
	v_mov_b32_e32 v112, v2
	v_mov_b32_e32 v113, v2
	v_mov_b32_e32 v122, v2
	v_mov_b32_e32 v123, v2
	v_mov_b32_e32 v124, v2
	v_mov_b32_e32 v125, v2
	v_mov_b32_e32 v126, v2
	v_mov_b32_e32 v127, v2
	v_mov_b32_e32 v128, v2
	v_mov_b32_e32 v129, v2
	s_lshl_b32 s98, s68, 8
	s_add_i32 s98, s98, s60
	v_or_b32_e32 v154, s98, v145
	v_ashrrev_i32_e32 v155, 31, v154
	v_lshl_add_u64 v[154:155], v[154:155], 2, s[2:3]
	global_load_dword v140, v[154:155], off
	v_add_u32_e32 v154, s98, v147
	v_ashrrev_i32_e32 v155, 31, v154
	v_lshl_add_u64 v[154:155], v[154:155], 2, s[2:3]
	global_load_dword v142, v[154:155], off
	v_add_u32_e32 v200, 0x10000, v143
	ds_read_b128 v[152:155], v200
	ds_read_b128 v[156:159], v200 offset:1024
	ds_read_b128 v[160:163], v200 offset:2048
	ds_read_b128 v[164:167], v200 offset:3072
.LBB0_90:
	s_add_u32 s48, s46, 0xfff80080
	s_addc_u32 s49, s47, -1
	s_add_i32 s74, 0, 0x10000
	s_cmp_eq_u32 s73, 28
	s_cselect_b32 s51, s41, s49
	s_cselect_b32 s50, s69, s48
	s_cselect_b32 s49, s39, s72
	s_cselect_b32 s48, s70, s71
	s_add_i32 m0, s56, 0xc000
	ds_read_b128 v[168:171], v151
	ds_read_b128 v[172:175], v151 offset:1024
	ds_read_b128 v[176:179], v151 offset:2048
	ds_read_b128 v[180:183], v151 offset:3072
	ds_read_b128 v[184:187], v151 offset:4096
	ds_read_b128 v[188:191], v151 offset:5120
	ds_read_b128 v[192:195], v151 offset:6144
	ds_read_b128 v[196:199], v151 offset:7168
	global_load_lds_dwordx4 v136, s[46:47]
	s_add_i32 m0, s56, 0xe000
	s_waitcnt lgkmcnt(8)
	global_load_lds_dwordx4 v138, s[46:47]
	s_barrier
	s_waitcnt lgkmcnt(0)
	v_mfma_f32_16x16x32_bf16 v[126:129], v[152:155], v[168:171], v[126:129]
	v_mfma_f32_16x16x32_bf16 v[122:125], v[160:163], v[168:171], v[122:125]
	v_mfma_f32_16x16x32_bf16 v[110:113], v[152:155], v[176:179], v[110:113]
	v_mfma_f32_16x16x32_bf16 v[102:105], v[160:163], v[176:179], v[102:105]
	v_mfma_f32_16x16x32_bf16 v[94:97], v[152:155], v[184:187], v[94:97]
	v_mfma_f32_16x16x32_bf16 v[86:89], v[160:163], v[184:187], v[86:89]
	v_mfma_f32_16x16x32_bf16 v[78:81], v[152:155], v[192:195], v[78:81]
	v_mfma_f32_16x16x32_bf16 v[70:73], v[160:163], v[192:195], v[70:73]
	v_mfma_f32_16x16x32_bf16 v[126:129], v[156:159], v[172:175], v[126:129]
	v_mfma_f32_16x16x32_bf16 v[122:125], v[164:167], v[172:175], v[122:125]
	v_mfma_f32_16x16x32_bf16 v[110:113], v[156:159], v[180:183], v[110:113]
	v_mfma_f32_16x16x32_bf16 v[102:105], v[164:167], v[180:183], v[102:105]
	v_mfma_f32_16x16x32_bf16 v[94:97], v[156:159], v[188:191], v[94:97]
	v_mfma_f32_16x16x32_bf16 v[86:89], v[164:167], v[188:191], v[86:89]
	v_mfma_f32_16x16x32_bf16 v[78:81], v[156:159], v[196:199], v[78:81]
	v_mfma_f32_16x16x32_bf16 v[70:73], v[164:167], v[196:199], v[70:73]
	s_barrier
; #define PG8_STAGE(bufoff, gbase, voff) do { _Pragma("unroll") for (int _i = 0; _i < 2; ++_i) \
;         __builtin_amdgcn_global_load_lds((const unsigned*)((const char*)(gbase) + (voff)[_i]), (LAS unsigned*)(lds + (bufoff) + ldsw + _i * 8192), 16, 0, 0); } while (0)
; #define PG8_LDA(dst, b, h) do { _Pragma("unroll") for (int m = 0; m < 4; ++m) _Pragma("unroll") for (int k = 0; k < 2; ++k) dst[m][k] = *(const LAS bf16x8*)(lds + PG8_SA(b, h) + aoff + m * 2048 + k * 1024); } while (0)
; #define PG8_LDB(dst, b, h) do { _Pragma("unroll") for (int n = 0; n < 2; ++n) _Pragma("unroll") for (int k = 0; k < 2; ++k) dst[n][k] = *(const LAS bf16x8*)(lds + PG8_SB(b, h) + boff + n * 2048 + k * 1024); } while (0)
; #define PG8_MMA(ai, bj, At, Bt) do { __builtin_amdgcn_s_setprio(1); _Pragma("unroll") for (int m = 0; m < 4; ++m) _Pragma("unroll") for (int n = 0; n < 2; ++n) _Pragma("unroll") for (int k = 0; k < 2; ++k) \
;         acc[ai][bj][m][n] = __builtin_amdgcn_mfma_f32_16x16x32_bf16(Bt[n][k], At[m][k], acc[ai][bj][m][n], 0, 0, 0); __builtin_amdgcn_s_setprio(0); } while (0)
; #define PG8_WAIT_V(n) asm volatile("s_waitcnt vmcnt(" #n ")" ::: "memory")
; #define PG8_WAIT_L(n) asm volatile("s_waitcnt lgkmcnt(" #n ")" ::: "memory")
; #define PG8_BAR __builtin_amdgcn_s_barrier()
; #define PG8_SCHED __builtin_amdgcn_sched_barrier(0)
; template <class Epi>
; __device__ __forceinline__ void gemm_phase(LAS unsigned char* lds, const Gemm g, const StaticOrder& S, const Epi& E) {
;     ...
;             PG8_LDB(B1, 0, 1); PG8_STAGE(PG8_SB(0, 0), b2, voffB);
;             PG8_BAR; PG8_WAIT_L(0); PG8_MMA(0, 1, At, B1); PG8_BAR;
;             PG8_LDA(At, 0, 1); PG8_STAGE(PG8_SA(0, 0), a2, voffA);
;             PG8_BAR; PG8_WAIT_L(0); PG8_MMA(1, 0, At, B0); PG8_BAR; PG8_SCHED;
;             PG8_STAGE(PG8_SB(0, 1), b2 + hstep, voffB);
;             PG8_WAIT_V(6); PG8_BAR; PG8_MMA(1, 1, At, B1); PG8_BAR;
;             PG8_LDB(B0, 1, 0); PG8_SCHED; PG8_LDA(At, 1, 0); PG8_STAGE(PG8_SA(0, 1), a2 + hstep, voffA);
;             PG8_WAIT_L(8); PG8_BAR; PG8_WAIT_L(0); PG8_MMA(0, 0, At, B0); PG8_BAR; PG8_SCHED;
;             PG8_LDB(B1, 1, 1); PG8_STAGE(PG8_SB(1, 0), b3, voffB);
	s_add_i32 s76, 0, 0x14000
	s_add_i32 s74, s74, s55
	s_mov_b32 m0, s74
	ds_read_b128 v[208:211], v200 offset:16384
	ds_read_b128 v[212:215], v200 offset:17408
	ds_read_b128 v[216:219], v200 offset:18432
	ds_read_b128 v[220:223], v200 offset:19456
	global_load_lds_dwordx4 v0, s[48:49]
	s_add_i32 m0, s74, 0x2000
	s_add_u32 s98, s48, s22
	global_load_lds_dwordx4 v130, s[48:49]
	s_addc_u32 s99, s49, s23
	s_barrier
	s_waitcnt lgkmcnt(0)
	v_mfma_f32_16x16x32_bf16 v[118:121], v[208:211], v[168:171], v[118:121]
	v_mfma_f32_16x16x32_bf16 v[114:117], v[216:219], v[168:171], v[114:117]
	v_mfma_f32_16x16x32_bf16 v[106:109], v[208:211], v[176:179], v[106:109]
	v_mfma_f32_16x16x32_bf16 v[98:101], v[216:219], v[176:179], v[98:101]
	v_mfma_f32_16x16x32_bf16 v[90:93], v[208:211], v[184:187], v[90:93]
	v_mfma_f32_16x16x32_bf16 v[82:85], v[216:219], v[184:187], v[82:85]
	v_mfma_f32_16x16x32_bf16 v[74:77], v[208:211], v[192:195], v[74:77]
	v_mfma_f32_16x16x32_bf16 v[66:69], v[216:219], v[192:195], v[66:69]
	v_mfma_f32_16x16x32_bf16 v[118:121], v[212:215], v[172:175], v[118:121]
	v_mfma_f32_16x16x32_bf16 v[114:117], v[220:223], v[172:175], v[114:117]
	v_mfma_f32_16x16x32_bf16 v[106:109], v[212:215], v[180:183], v[106:109]
	v_mfma_f32_16x16x32_bf16 v[98:101], v[220:223], v[180:183], v[98:101]
	v_mfma_f32_16x16x32_bf16 v[90:93], v[212:215], v[188:191], v[90:93]
	v_mfma_f32_16x16x32_bf16 v[82:85], v[220:223], v[188:191], v[82:85]
	v_mfma_f32_16x16x32_bf16 v[74:77], v[212:215], v[196:199], v[74:77]
	v_mfma_f32_16x16x32_bf16 v[66:69], v[220:223], v[196:199], v[66:69]
	s_barrier
	ds_read_b128 v[168:171], v151 offset:16384
	ds_read_b128 v[172:175], v151 offset:17408
	ds_read_b128 v[176:179], v151 offset:18432
	ds_read_b128 v[180:183], v151 offset:19456
	ds_read_b128 v[184:187], v151 offset:20480
	ds_read_b128 v[188:191], v151 offset:21504
	ds_read_b128 v[192:195], v151 offset:22528
	s_mov_b32 m0, s56
	s_add_u32 s100, s50, s22
	s_addc_u32 s101, s51, s23
	ds_read_b128 v[196:199], v151 offset:23552
	global_load_lds_dwordx4 v134, s[50:51]
	s_mov_b32 m0, s57
	s_waitcnt vmcnt(9)
	global_load_lds_dwordx4 v132, s[50:51]
	s_barrier
	s_waitcnt lgkmcnt(0)
	v_mfma_f32_16x16x32_bf16 v[62:65], v[152:155], v[168:171], v[62:65]
	v_mfma_f32_16x16x32_bf16 v[54:57], v[160:163], v[168:171], v[54:57]
	v_mfma_f32_16x16x32_bf16 v[46:49], v[152:155], v[176:179], v[46:49]
	v_mfma_f32_16x16x32_bf16 v[38:41], v[160:163], v[176:179], v[38:41]
	v_mfma_f32_16x16x32_bf16 v[30:33], v[152:155], v[184:187], v[30:33]
	v_mfma_f32_16x16x32_bf16 v[22:25], v[160:163], v[184:187], v[22:25]
	v_mfma_f32_16x16x32_bf16 v[14:17], v[152:155], v[192:195], v[14:17]
	v_mfma_f32_16x16x32_bf16 v[6:9], v[160:163], v[192:195], v[6:9]
	v_mfma_f32_16x16x32_bf16 v[62:65], v[156:159], v[172:175], v[62:65]
	v_mfma_f32_16x16x32_bf16 v[54:57], v[164:167], v[172:175], v[54:57]
	v_mfma_f32_16x16x32_bf16 v[46:49], v[156:159], v[180:183], v[46:49]
	v_mfma_f32_16x16x32_bf16 v[38:41], v[164:167], v[180:183], v[38:41]
	v_mfma_f32_16x16x32_bf16 v[30:33], v[156:159], v[188:191], v[30:33]
	v_mfma_f32_16x16x32_bf16 v[22:25], v[164:167], v[188:191], v[22:25]
	v_mfma_f32_16x16x32_bf16 v[14:17], v[156:159], v[196:199], v[14:17]
	v_mfma_f32_16x16x32_bf16 v[6:9], v[164:167], v[196:199], v[6:9]
	s_barrier
	ds_read_b128 v[152:155], v200 offset:32768
	ds_read_b128 v[156:159], v200 offset:33792
	ds_read_b128 v[160:163], v200 offset:34816
	ds_read_b128 v[164:167], v200 offset:35840
	s_add_i32 s76, s76, s55
	s_mov_b32 m0, s76
	s_add_u32 s74, s48, 0x80000
	s_addc_u32 s75, s49, 0
	global_load_lds_dwordx4 v0, s[74:75]
	s_add_i32 m0, s76, 0x2000
	s_waitcnt vmcnt(5)
	global_load_lds_dwordx4 v130, s[74:75]
	s_barrier
	v_mfma_f32_16x16x32_bf16 v[58:61], v[208:211], v[168:171], v[58:61]
	v_mfma_f32_16x16x32_bf16 v[50:53], v[216:219], v[168:171], v[50:53]
	v_mfma_f32_16x16x32_bf16 v[42:45], v[208:211], v[176:179], v[42:45]
	v_mfma_f32_16x16x32_bf16 v[34:37], v[216:219], v[176:179], v[34:37]
	v_mfma_f32_16x16x32_bf16 v[26:29], v[208:211], v[184:187], v[26:29]
	v_mfma_f32_16x16x32_bf16 v[18:21], v[216:219], v[184:187], v[18:21]
	v_mfma_f32_16x16x32_bf16 v[10:13], v[208:211], v[192:195], v[10:13]
	v_mfma_f32_16x16x32_bf16 v[2:5], v[216:219], v[192:195], v[2:5]
	v_mfma_f32_16x16x32_bf16 v[58:61], v[212:215], v[172:175], v[58:61]
	v_mfma_f32_16x16x32_bf16 v[50:53], v[220:223], v[172:175], v[50:53]
	v_mfma_f32_16x16x32_bf16 v[42:45], v[212:215], v[180:183], v[42:45]
	v_mfma_f32_16x16x32_bf16 v[34:37], v[220:223], v[180:183], v[34:37]
	v_mfma_f32_16x16x32_bf16 v[26:29], v[212:215], v[188:191], v[26:29]
	v_mfma_f32_16x16x32_bf16 v[18:21], v[220:223], v[188:191], v[18:21]
	v_mfma_f32_16x16x32_bf16 v[10:13], v[212:215], v[196:199], v[10:13]
	v_mfma_f32_16x16x32_bf16 v[2:5], v[220:223], v[196:199], v[2:5]
	s_barrier
	s_add_u32 s50, s50, 0x80000
	s_addc_u32 s51, s51, 0
	s_mov_b32 m0, s58
	ds_read_b128 v[168:171], v151 offset:32768
	ds_read_b128 v[172:175], v151 offset:33792
	ds_read_b128 v[176:179], v151 offset:34816
	ds_read_b128 v[180:183], v151 offset:35840
	ds_read_b128 v[184:187], v151 offset:36864
	ds_read_b128 v[188:191], v151 offset:37888
	ds_read_b128 v[192:195], v151 offset:38912
	s_add_i32 s74, 0, 0x18000
	ds_read_b128 v[196:199], v151 offset:39936
	global_load_lds_dwordx4 v134, s[50:51]
	s_mov_b32 m0, s59
	s_waitcnt lgkmcnt(8)
	global_load_lds_dwordx4 v132, s[50:51]
	s_barrier
; #define PG8_STAGE(bufoff, gbase, voff) do { _Pragma("unroll") for (int _i = 0; _i < 2; ++_i) \
;         __builtin_amdgcn_global_load_lds((const unsigned*)((const char*)(gbase) + (voff)[_i]), (LAS unsigned*)(lds + (bufoff) + ldsw + _i * 8192), 16, 0, 0); } while (0)
; #define PG8_LDA(dst, b, h) do { _Pragma("unroll") for (int m = 0; m < 4; ++m) _Pragma("unroll") for (int k = 0; k < 2; ++k) dst[m][k] = *(const LAS bf16x8*)(lds + PG8_SA(b, h) + aoff + m * 2048 + k * 1024); } while (0)
; #define PG8_LDB(dst, b, h) do { _Pragma("unroll") for (int n = 0; n < 2; ++n) _Pragma("unroll") for (int k = 0; k < 2; ++k) dst[n][k] = *(const LAS bf16x8*)(lds + PG8_SB(b, h) + boff + n * 2048 + k * 1024); } while (0)
; #define PG8_MMA(ai, bj, At, Bt) do { __builtin_amdgcn_s_setprio(1); _Pragma("unroll") for (int m = 0; m < 4; ++m) _Pragma("unroll") for (int n = 0; n < 2; ++n) _Pragma("unroll") for (int k = 0; k < 2; ++k) \
;         acc[ai][bj][m][n] = __builtin_amdgcn_mfma_f32_16x16x32_bf16(Bt[n][k], At[m][k], acc[ai][bj][m][n], 0, 0, 0); __builtin_amdgcn_s_setprio(0); } while (0)
; #define PG8_WAIT_V(n) asm volatile("s_waitcnt vmcnt(" #n ")" ::: "memory")
; #define PG8_WAIT_L(n) asm volatile("s_waitcnt lgkmcnt(" #n ")" ::: "memory")
; #define PG8_BAR __builtin_amdgcn_s_barrier()
; #define PG8_SCHED __builtin_amdgcn_sched_barrier(0)
; template <class Epi>
; __device__ __forceinline__ void gemm_phase(LAS unsigned char* lds, const Gemm g, const StaticOrder& S, const Epi& E) {
;     ...
;             PG8_LDB(B1, 1, 1); PG8_STAGE(PG8_SB(1, 0), b3, voffB);
;             PG8_BAR; PG8_WAIT_L(0); PG8_MMA(0, 1, At, B1); PG8_BAR;
;             PG8_LDA(At, 1, 1); PG8_STAGE(PG8_SA(1, 0), a3, voffA);
;             PG8_BAR; PG8_WAIT_L(0); PG8_MMA(1, 0, At, B0); PG8_BAR; PG8_SCHED;
;             PG8_STAGE(PG8_SB(1, 1), b3 + hstep, voffB);
;             PG8_WAIT_V(6); PG8_BAR; PG8_MMA(1, 1, At, B1); PG8_BAR;
	s_waitcnt lgkmcnt(0)
	v_mfma_f32_16x16x32_bf16 v[126:129], v[152:155], v[168:171], v[126:129]
	v_mfma_f32_16x16x32_bf16 v[122:125], v[160:163], v[168:171], v[122:125]
	v_mfma_f32_16x16x32_bf16 v[110:113], v[152:155], v[176:179], v[110:113]
	v_mfma_f32_16x16x32_bf16 v[102:105], v[160:163], v[176:179], v[102:105]
	v_mfma_f32_16x16x32_bf16 v[94:97], v[152:155], v[184:187], v[94:97]
	v_mfma_f32_16x16x32_bf16 v[86:89], v[160:163], v[184:187], v[86:89]
	v_mfma_f32_16x16x32_bf16 v[78:81], v[152:155], v[192:195], v[78:81]
	v_mfma_f32_16x16x32_bf16 v[70:73], v[160:163], v[192:195], v[70:73]
	v_mfma_f32_16x16x32_bf16 v[126:129], v[156:159], v[172:175], v[126:129]
	v_mfma_f32_16x16x32_bf16 v[122:125], v[164:167], v[172:175], v[122:125]
	v_mfma_f32_16x16x32_bf16 v[110:113], v[156:159], v[180:183], v[110:113]
	v_mfma_f32_16x16x32_bf16 v[102:105], v[164:167], v[180:183], v[102:105]
	v_mfma_f32_16x16x32_bf16 v[94:97], v[156:159], v[188:191], v[94:97]
	v_mfma_f32_16x16x32_bf16 v[86:89], v[164:167], v[188:191], v[86:89]
	v_mfma_f32_16x16x32_bf16 v[78:81], v[156:159], v[196:199], v[78:81]
	v_mfma_f32_16x16x32_bf16 v[70:73], v[164:167], v[196:199], v[70:73]
	s_barrier
	s_add_i32 s51, s74, s55
	s_mov_b32 m0, s51
	ds_read_b128 v[208:211], v200 offset:49152
	ds_read_b128 v[212:215], v200 offset:50176
	ds_read_b128 v[216:219], v200 offset:51200
	ds_read_b128 v[220:223], v200 offset:52224
	global_load_lds_dwordx4 v0, s[98:99]
	s_add_i32 m0, s51, 0x2000
	s_add_i32 s50, 0, 0x1c000
	global_load_lds_dwordx4 v130, s[98:99]
	s_barrier
	s_waitcnt lgkmcnt(0)
	v_mfma_f32_16x16x32_bf16 v[118:121], v[208:211], v[168:171], v[118:121]
	v_mfma_f32_16x16x32_bf16 v[114:117], v[216:219], v[168:171], v[114:117]
	v_mfma_f32_16x16x32_bf16 v[106:109], v[208:211], v[176:179], v[106:109]
	v_mfma_f32_16x16x32_bf16 v[98:101], v[216:219], v[176:179], v[98:101]
	v_mfma_f32_16x16x32_bf16 v[90:93], v[208:211], v[184:187], v[90:93]
	v_mfma_f32_16x16x32_bf16 v[82:85], v[216:219], v[184:187], v[82:85]
	v_mfma_f32_16x16x32_bf16 v[74:77], v[208:211], v[192:195], v[74:77]
	v_mfma_f32_16x16x32_bf16 v[66:69], v[216:219], v[192:195], v[66:69]
	v_mfma_f32_16x16x32_bf16 v[118:121], v[212:215], v[172:175], v[118:121]
	v_mfma_f32_16x16x32_bf16 v[114:117], v[220:223], v[172:175], v[114:117]
	v_mfma_f32_16x16x32_bf16 v[106:109], v[212:215], v[180:183], v[106:109]
	v_mfma_f32_16x16x32_bf16 v[98:101], v[220:223], v[180:183], v[98:101]
	v_mfma_f32_16x16x32_bf16 v[90:93], v[212:215], v[188:191], v[90:93]
	v_mfma_f32_16x16x32_bf16 v[82:85], v[220:223], v[188:191], v[82:85]
	v_mfma_f32_16x16x32_bf16 v[74:77], v[212:215], v[196:199], v[74:77]
	v_mfma_f32_16x16x32_bf16 v[66:69], v[220:223], v[196:199], v[66:69]
	s_barrier
	ds_read_b128 v[168:171], v151 offset:49152
	ds_read_b128 v[172:175], v151 offset:50176
	ds_read_b128 v[176:179], v151 offset:51200
	ds_read_b128 v[180:183], v151 offset:52224
	ds_read_b128 v[184:187], v151 offset:53248
	ds_read_b128 v[188:191], v151 offset:54272
	ds_read_b128 v[192:195], v151 offset:55296
	s_mov_b32 m0, s61
	ds_read_b128 v[196:199], v151 offset:56320
	global_load_lds_dwordx4 v134, s[100:101]
	s_mov_b32 m0, s63
	s_waitcnt vmcnt(9)
	global_load_lds_dwordx4 v132, s[100:101]
	s_barrier
	s_waitcnt lgkmcnt(0)
	v_mfma_f32_16x16x32_bf16 v[62:65], v[152:155], v[168:171], v[62:65]
	v_mfma_f32_16x16x32_bf16 v[54:57], v[160:163], v[168:171], v[54:57]
	v_mfma_f32_16x16x32_bf16 v[46:49], v[152:155], v[176:179], v[46:49]
	v_mfma_f32_16x16x32_bf16 v[38:41], v[160:163], v[176:179], v[38:41]
	v_mfma_f32_16x16x32_bf16 v[30:33], v[152:155], v[184:187], v[30:33]
	v_mfma_f32_16x16x32_bf16 v[22:25], v[160:163], v[184:187], v[22:25]
	v_mfma_f32_16x16x32_bf16 v[14:17], v[152:155], v[192:195], v[14:17]
	v_mfma_f32_16x16x32_bf16 v[6:9], v[160:163], v[192:195], v[6:9]
	v_mfma_f32_16x16x32_bf16 v[62:65], v[156:159], v[172:175], v[62:65]
	v_mfma_f32_16x16x32_bf16 v[54:57], v[164:167], v[172:175], v[54:57]
	v_mfma_f32_16x16x32_bf16 v[46:49], v[156:159], v[180:183], v[46:49]
	v_mfma_f32_16x16x32_bf16 v[38:41], v[164:167], v[180:183], v[38:41]
	v_mfma_f32_16x16x32_bf16 v[30:33], v[156:159], v[188:191], v[30:33]
	v_mfma_f32_16x16x32_bf16 v[22:25], v[164:167], v[188:191], v[22:25]
	v_mfma_f32_16x16x32_bf16 v[14:17], v[156:159], v[196:199], v[14:17]
	v_mfma_f32_16x16x32_bf16 v[6:9], v[164:167], v[196:199], v[6:9]
	s_barrier
	ds_read_b128 v[152:155], v200
	ds_read_b128 v[156:159], v200 offset:1024
	ds_read_b128 v[160:163], v200 offset:2048
	s_add_i32 s73, s73, 2
	s_add_u32 s46, s46, 0x100
	s_addc_u32 s47, s47, 0
	s_add_u32 s71, s71, 0x100
	s_addc_u32 s72, s72, 0
	ds_read_b128 v[164:167], v200 offset:3072
	s_add_i32 s50, s50, s55
	s_mov_b32 m0, s50
	s_add_u32 s48, s48, 0x80080
	s_addc_u32 s49, s49, 0
	global_load_lds_dwordx4 v0, s[48:49]
	s_add_i32 m0, s50, 0x2000
	s_waitcnt vmcnt(5)
	global_load_lds_dwordx4 v130, s[48:49]
	s_barrier
	v_mfma_f32_16x16x32_bf16 v[58:61], v[208:211], v[168:171], v[58:61]
	v_mfma_f32_16x16x32_bf16 v[50:53], v[216:219], v[168:171], v[50:53]
	v_mfma_f32_16x16x32_bf16 v[42:45], v[208:211], v[176:179], v[42:45]
	v_mfma_f32_16x16x32_bf16 v[34:37], v[216:219], v[176:179], v[34:37]
	v_mfma_f32_16x16x32_bf16 v[26:29], v[208:211], v[184:187], v[26:29]
	v_mfma_f32_16x16x32_bf16 v[18:21], v[216:219], v[184:187], v[18:21]
	v_mfma_f32_16x16x32_bf16 v[10:13], v[208:211], v[192:195], v[10:13]
	v_mfma_f32_16x16x32_bf16 v[2:5], v[216:219], v[192:195], v[2:5]
	v_mfma_f32_16x16x32_bf16 v[58:61], v[212:215], v[172:175], v[58:61]
	v_mfma_f32_16x16x32_bf16 v[50:53], v[220:223], v[172:175], v[50:53]
	v_mfma_f32_16x16x32_bf16 v[42:45], v[212:215], v[180:183], v[42:45]
	v_mfma_f32_16x16x32_bf16 v[34:37], v[220:223], v[180:183], v[34:37]
	v_mfma_f32_16x16x32_bf16 v[26:29], v[212:215], v[188:191], v[26:29]
	v_mfma_f32_16x16x32_bf16 v[18:21], v[220:223], v[188:191], v[18:21]
	v_mfma_f32_16x16x32_bf16 v[10:13], v[212:215], v[196:199], v[10:13]
	v_mfma_f32_16x16x32_bf16 v[2:5], v[220:223], v[196:199], v[2:5]
	s_cmp_gt_u32 s73, 29
	s_barrier
; __device__ __forceinline__ unsigned pk2(float lo, float hi) { f32x2 v = {lo, hi}; bf16x2_t b = __builtin_convertvector(v, bf16x2_t); return __builtin_bit_cast(unsigned, b); }
;     __device__ __forceinline__ void operator()(const AccT& acc, const Unit& u, int wr, int wc, int fr, int fq) const {
;     ...
;             const int ln = (fq << 4) | fr;
;             float sa = ss[u.pm * BM + wr * 64 + ln], sb = ss[u.pm * BM + HALF + wr * 64 + ln];
;             sa = __builtin_amdgcn_rsqf(sa * (1.0f / DM) + EPS); sb = __builtin_amdgcn_rsqf(sb * (1.0f / DM) + EPS);
; #pragma unroll
;             for (int m = 0; m < 4; ++m) { rsv[m] = __shfl(sa, 16 * m + fr); rsv[4 + m] = __shfl(sb, 16 * m + fr); }
;         }
; #pragma unroll
;         for (int ai = 0; ai < 2; ++ai)
; #pragma unroll
;             for (int m = 0; m < 4; ++m) {
;                 const int row = row0 + ai * HALF + m * 16;
;                 const float rs = rsv[ai * 4 + m];
;                 float v[8];
; #pragma unroll
;                 for (int n = 0; n < 2; ++n)
; #pragma unroll
;                     for (int j = 0; j < 4; ++j) {
;                         const float g = acc[ai][0][m][n][j] * rs, up = acc[ai][1][m][n][j] * rs;
;                         const float sg = __builtin_amdgcn_rcpf(1.0f + __builtin_amdgcn_exp2f(-g * LOG2E));
;                         v[4 * n + j] = g * sg * up;
;                     }
;                 u32x4 w; w.x = pk2(v[0], v[1]); w.y = pk2(v[2], v[3]); w.z = pk2(v[4], v[5]); w.w = pk2(v[6], v[7]);
;                 *(u32x4*)(mid + (size_t)row * FF + col0) = w;
	s_cbranch_scc0 .LBB0_90
	s_waitcnt lgkmcnt(0)
	s_lshl_b32 s39, s68, 8
	s_add_i32 s39, s39, s60
	v_readlane_b32 s46, v251, 58
	v_readlane_b32 s47, v251, 59
	v_or_b32_e32 v153, s39, v141
	s_movk_i32 s39, 0x2c00
	s_and_b64 vcc, exec, s[36:37]
	s_mov_b32 s68, s40
	s_mov_b64 s[48:49], s[44:45]
	v_fmamk_f32 v140, v140, 0x3a000000, v233
	v_rsq_f32_e32 v140, v140
	v_fmamk_f32 v142, v142, 0x3a000000, v233
	v_rsq_f32_e32 v154, v142
	v_and_or_b32 v142, v234, 64, v141
	v_lshlrev_b32_e32 v155, 2, v142
	ds_bpermute_b32 v156, v155, v140
	ds_bpermute_b32 v152, v155, v140 offset:64
	ds_bpermute_b32 v146, v155, v154
	ds_bpermute_b32 v144, v155, v154 offset:64
	ds_bpermute_b32 v150, v155, v140 offset:128
	s_waitcnt lgkmcnt(0)
	v_pk_mul_f32 v[126:127], v[126:127], v[156:157] op_sel_hi:[1,0]
	ds_bpermute_b32 v142, v155, v154 offset:128
	v_mul_f32_e32 v157, 0xbfb8aa3b, v126
	v_exp_f32_e32 v157, v157
	ds_bpermute_b32 v148, v155, v140 offset:192
	ds_bpermute_b32 v140, v155, v154 offset:192
	v_lshl_or_b32 v154, s65, 7, v149
	v_add_f32_e32 v157, 1.0, v157
	v_rcp_f32_e32 v158, v157
	v_pk_mul_f32 v[118:119], v[118:119], v[156:157] op_sel_hi:[1,0]
	v_mul_f32_e32 v157, 0xbfb8aa3b, v127
	v_exp_f32_e32 v157, v157
	v_ashrrev_i32_e32 v155, 31, v154
	v_pk_mul_f32 v[110:111], v[110:111], v[152:153] op_sel_hi:[1,0]
	v_pk_mul_f32 v[106:107], v[106:107], v[152:153] op_sel_hi:[1,0]
	v_add_f32_e32 v157, 1.0, v157
	v_rcp_f32_e32 v159, v157
	v_pk_mul_f32 v[120:121], v[120:121], v[156:157] op_sel_hi:[1,0]
	v_pk_mul_f32 v[122:123], v[122:123], v[156:157] op_sel_hi:[1,0]
	v_pk_mul_f32 v[114:115], v[114:115], v[156:157] op_sel_hi:[1,0]
	v_pk_mul_f32 v[126:127], v[126:127], v[158:159]
	v_pk_mul_f32 v[116:117], v[116:117], v[156:157] op_sel_hi:[1,0]
	v_pk_mul_f32 v[118:119], v[118:119], v[126:127]
	v_pk_mul_f32 v[126:127], v[128:129], v[156:157] op_sel_hi:[1,0]
	v_pk_mul_f32 v[108:109], v[108:109], v[152:153] op_sel_hi:[1,0]
	v_mul_f32_e32 v128, 0xbfb8aa3b, v126
	v_mul_f32_e32 v129, 0xbfb8aa3b, v127
	v_exp_f32_e32 v128, v128
	v_exp_f32_e32 v129, v129
	v_pk_mul_f32 v[102:103], v[102:103], v[152:153] op_sel_hi:[1,0]
	v_pk_mul_f32 v[98:99], v[98:99], v[152:153] op_sel_hi:[1,0]
	v_add_f32_e32 v128, 1.0, v128
	v_add_f32_e32 v129, 1.0, v129
	v_rcp_f32_e32 v128, v128
	v_rcp_f32_e32 v129, v129
	v_pk_mul_f32 v[100:101], v[100:101], v[152:153] op_sel_hi:[1,0]
	v_pk_mul_f32 v[94:95], v[94:95], v[150:151] op_sel_hi:[1,0]
	v_pk_mul_f32 v[90:91], v[90:91], v[150:151] op_sel_hi:[1,0]
	v_pk_mul_f32 v[126:127], v[126:127], v[128:129]
	v_pk_mul_f32 v[92:93], v[92:93], v[150:151] op_sel_hi:[1,0]
	v_pk_mul_f32 v[120:121], v[120:121], v[126:127]
	v_mul_f32_e32 v126, 0xbfb8aa3b, v122
	v_mul_f32_e32 v127, 0xbfb8aa3b, v123
	v_exp_f32_e32 v126, v126
	v_exp_f32_e32 v127, v127
	v_pk_mul_f32 v[86:87], v[86:87], v[150:151] op_sel_hi:[1,0]
	v_pk_mul_f32 v[82:83], v[82:83], v[150:151] op_sel_hi:[1,0]
	v_add_f32_e32 v126, 1.0, v126
	v_add_f32_e32 v127, 1.0, v127
	v_rcp_f32_e32 v126, v126
	v_rcp_f32_e32 v127, v127
	v_pk_mul_f32 v[84:85], v[84:85], v[150:151] op_sel_hi:[1,0]
	s_waitcnt lgkmcnt(1)
	v_pk_mul_f32 v[78:79], v[78:79], v[148:149] op_sel_hi:[1,0]
	v_pk_mul_f32 v[74:75], v[74:75], v[148:149] op_sel_hi:[1,0]
	v_pk_mul_f32 v[122:123], v[122:123], v[126:127]
	v_pk_mul_f32 v[76:77], v[76:77], v[148:149] op_sel_hi:[1,0]
	v_pk_mul_f32 v[122:123], v[114:115], v[122:123]
	v_pk_mul_f32 v[114:115], v[124:125], v[156:157] op_sel_hi:[1,0]
	v_pk_mul_f32 v[70:71], v[70:71], v[148:149] op_sel_hi:[1,0]
	v_mul_f32_e32 v124, 0xbfb8aa3b, v114
	v_mul_f32_e32 v125, 0xbfb8aa3b, v115
	v_exp_f32_e32 v124, v124
	v_exp_f32_e32 v125, v125
	v_pk_mul_f32 v[66:67], v[66:67], v[148:149] op_sel_hi:[1,0]
	v_pk_mul_f32 v[68:69], v[68:69], v[148:149] op_sel_hi:[1,0]
	v_add_f32_e32 v124, 1.0, v124
	v_add_f32_e32 v125, 1.0, v125
	v_rcp_f32_e32 v124, v124
	v_rcp_f32_e32 v125, v125
	v_pk_mul_f32 v[62:63], v[62:63], v[146:147] op_sel_hi:[1,0]
	v_pk_mul_f32 v[58:59], v[58:59], v[146:147] op_sel_hi:[1,0]
	v_pk_mul_f32 v[60:61], v[60:61], v[146:147] op_sel_hi:[1,0]
	v_pk_mul_f32 v[114:115], v[114:115], v[124:125]
	v_pk_mul_f32 v[54:55], v[54:55], v[146:147] op_sel_hi:[1,0]
	v_pk_mul_f32 v[124:125], v[116:117], v[114:115]
	v_cvt_pk_bf16_f32 v114, v118, v119
	v_mov_b64_e32 v[118:119], s[46:47]
	v_cvt_pk_bf16_f32 v115, v120, v121
	v_cvt_pk_bf16_f32 v116, v122, v123
	v_mad_i64_i32 v[122:123], s[46:47], v153, s39, v[118:119]
	v_lshlrev_b64 v[120:121], 1, v[154:155]
	v_cvt_pk_bf16_f32 v117, v124, v125
	v_lshl_add_u64 v[122:123], v[122:123], 0, v[120:121]
	global_store_dwordx4 v[122:123], v[114:117], off
	v_pk_mul_f32 v[50:51], v[50:51], v[146:147] op_sel_hi:[1,0]
	v_pk_mul_f32 v[52:53], v[52:53], v[146:147] op_sel_hi:[1,0]
	v_mul_f32_e32 v114, 0xbfb8aa3b, v110
	v_mul_f32_e32 v115, 0xbfb8aa3b, v111
	v_exp_f32_e32 v114, v114
	v_exp_f32_e32 v115, v115
	v_pk_mul_f32 v[46:47], v[46:47], v[144:145] op_sel_hi:[1,0]
	v_pk_mul_f32 v[42:43], v[42:43], v[144:145] op_sel_hi:[1,0]
	v_add_f32_e32 v114, 1.0, v114
	v_add_f32_e32 v115, 1.0, v115
	v_rcp_f32_e32 v114, v114
	v_rcp_f32_e32 v115, v115
	v_pk_mul_f32 v[44:45], v[44:45], v[144:145] op_sel_hi:[1,0]
	v_pk_mul_f32 v[38:39], v[38:39], v[144:145] op_sel_hi:[1,0]
	v_pk_mul_f32 v[34:35], v[34:35], v[144:145] op_sel_hi:[1,0]
	v_pk_mul_f32 v[110:111], v[110:111], v[114:115]
	v_pk_mul_f32 v[36:37], v[36:37], v[144:145] op_sel_hi:[1,0]
	v_pk_mul_f32 v[106:107], v[106:107], v[110:111]
	v_pk_mul_f32 v[110:111], v[112:113], v[152:153] op_sel_hi:[1,0]
	v_pk_mul_f32 v[30:31], v[30:31], v[142:143] op_sel_hi:[1,0]
	v_mul_f32_e32 v112, 0xbfb8aa3b, v110
	v_mul_f32_e32 v113, 0xbfb8aa3b, v111
	v_exp_f32_e32 v112, v112
	v_exp_f32_e32 v113, v113
	v_pk_mul_f32 v[26:27], v[26:27], v[142:143] op_sel_hi:[1,0]
	v_pk_mul_f32 v[28:29], v[28:29], v[142:143] op_sel_hi:[1,0]
	v_add_f32_e32 v112, 1.0, v112
	v_add_f32_e32 v113, 1.0, v113
	v_rcp_f32_e32 v112, v112
	v_rcp_f32_e32 v113, v113
	v_pk_mul_f32 v[22:23], v[22:23], v[142:143] op_sel_hi:[1,0]
	v_pk_mul_f32 v[18:19], v[18:19], v[142:143] op_sel_hi:[1,0]
	v_pk_mul_f32 v[20:21], v[20:21], v[142:143] op_sel_hi:[1,0]
	v_pk_mul_f32 v[110:111], v[110:111], v[112:113]
	s_waitcnt lgkmcnt(0)
; __device__ __forceinline__ unsigned pk2(float lo, float hi) { f32x2 v = {lo, hi}; bf16x2_t b = __builtin_convertvector(v, bf16x2_t); return __builtin_bit_cast(unsigned, b); }
;     __device__ __forceinline__ void operator()(const AccT& acc, const Unit& u, int wr, int wc, int fr, int fq) const {
;     ...
; #pragma unroll
;         for (int ai = 0; ai < 2; ++ai)
; #pragma unroll
;             for (int m = 0; m < 4; ++m) {
;                 const int row = row0 + ai * HALF + m * 16;
;                 const float rs = rsv[ai * 4 + m];
;                 float v[8];
; #pragma unroll
;                 for (int n = 0; n < 2; ++n)
; #pragma unroll
;                     for (int j = 0; j < 4; ++j) {
;                         const float g = acc[ai][0][m][n][j] * rs, up = acc[ai][1][m][n][j] * rs;
;                         const float sg = __builtin_amdgcn_rcpf(1.0f + __builtin_amdgcn_exp2f(-g * LOG2E));
;                         v[4 * n + j] = g * sg * up;
;                     }
;                 u32x4 w; w.x = pk2(v[0], v[1]); w.y = pk2(v[2], v[3]); w.z = pk2(v[4], v[5]); w.w = pk2(v[6], v[7]);
;                 *(u32x4*)(mid + (size_t)row * FF + col0) = w;
	v_pk_mul_f32 v[14:15], v[14:15], v[140:141] op_sel_hi:[1,0]
	v_pk_mul_f32 v[108:109], v[108:109], v[110:111]
	v_mul_f32_e32 v110, 0xbfb8aa3b, v102
	v_mul_f32_e32 v111, 0xbfb8aa3b, v103
	v_exp_f32_e32 v110, v110
	v_exp_f32_e32 v111, v111
	v_pk_mul_f32 v[10:11], v[10:11], v[140:141] op_sel_hi:[1,0]
	v_pk_mul_f32 v[12:13], v[12:13], v[140:141] op_sel_hi:[1,0]
	v_add_f32_e32 v110, 1.0, v110
	v_add_f32_e32 v111, 1.0, v111
	v_rcp_f32_e32 v110, v110
	v_rcp_f32_e32 v111, v111
	v_pk_mul_f32 v[6:7], v[6:7], v[140:141] op_sel_hi:[1,0]
	v_pk_mul_f32 v[2:3], v[2:3], v[140:141] op_sel_hi:[1,0]
	v_pk_mul_f32 v[4:5], v[4:5], v[140:141] op_sel_hi:[1,0]
	v_pk_mul_f32 v[102:103], v[102:103], v[110:111]
	v_or_b32_e32 v110, 16, v153
	v_pk_mul_f32 v[102:103], v[98:99], v[102:103]
	v_pk_mul_f32 v[98:99], v[104:105], v[152:153] op_sel_hi:[1,0]
	s_mov_b32 s65, s38
	v_mul_f32_e32 v104, 0xbfb8aa3b, v98
	v_mul_f32_e32 v105, 0xbfb8aa3b, v99
	v_exp_f32_e32 v104, v104
	v_exp_f32_e32 v105, v105
	v_add_f32_e32 v104, 1.0, v104
	v_add_f32_e32 v105, 1.0, v105
	v_rcp_f32_e32 v104, v104
	v_rcp_f32_e32 v105, v105
	s_nop 0
	v_pk_mul_f32 v[98:99], v[98:99], v[104:105]
	s_nop 0
	v_pk_mul_f32 v[104:105], v[100:101], v[98:99]
	v_cvt_pk_bf16_f32 v100, v102, v103
	v_mad_i64_i32 v[102:103], s[46:47], v110, s39, v[118:119]
	v_cvt_pk_bf16_f32 v98, v106, v107
	v_cvt_pk_bf16_f32 v99, v108, v109
	v_cvt_pk_bf16_f32 v101, v104, v105
	v_lshl_add_u64 v[102:103], v[102:103], 0, v[120:121]
	global_store_dwordx4 v[102:103], v[98:101], off
	s_nop 1
	v_mul_f32_e32 v98, 0xbfb8aa3b, v94
	v_mul_f32_e32 v99, 0xbfb8aa3b, v95
	v_exp_f32_e32 v98, v98
	v_exp_f32_e32 v99, v99
	v_add_f32_e32 v98, 1.0, v98
	v_add_f32_e32 v99, 1.0, v99
	v_rcp_f32_e32 v98, v98
	v_rcp_f32_e32 v99, v99
	s_nop 0
	v_pk_mul_f32 v[94:95], v[94:95], v[98:99]
	s_nop 0
	v_pk_mul_f32 v[90:91], v[90:91], v[94:95]
	v_pk_mul_f32 v[94:95], v[96:97], v[150:151] op_sel_hi:[1,0]
	s_nop 0
	v_mul_f32_e32 v96, 0xbfb8aa3b, v94
	v_mul_f32_e32 v97, 0xbfb8aa3b, v95
	v_exp_f32_e32 v96, v96
	v_exp_f32_e32 v97, v97
	v_add_f32_e32 v96, 1.0, v96
	v_add_f32_e32 v97, 1.0, v97
	v_rcp_f32_e32 v96, v96
	v_rcp_f32_e32 v97, v97
	s_nop 0
	v_pk_mul_f32 v[94:95], v[94:95], v[96:97]
	s_nop 0
	v_pk_mul_f32 v[92:93], v[92:93], v[94:95]
	v_mul_f32_e32 v94, 0xbfb8aa3b, v86
	v_mul_f32_e32 v95, 0xbfb8aa3b, v87
	v_exp_f32_e32 v94, v94
	v_exp_f32_e32 v95, v95
	v_add_f32_e32 v94, 1.0, v94
	v_add_f32_e32 v95, 1.0, v95
	v_rcp_f32_e32 v94, v94
	v_rcp_f32_e32 v95, v95
	s_nop 0
	v_pk_mul_f32 v[86:87], v[86:87], v[94:95]
	s_nop 0
	v_pk_mul_f32 v[86:87], v[82:83], v[86:87]
	v_pk_mul_f32 v[82:83], v[88:89], v[150:151] op_sel_hi:[1,0]
	v_or_b32_e32 v94, 32, v153
	v_mul_f32_e32 v88, 0xbfb8aa3b, v82
	v_mul_f32_e32 v89, 0xbfb8aa3b, v83
	v_exp_f32_e32 v88, v88
	v_exp_f32_e32 v89, v89
	v_add_f32_e32 v88, 1.0, v88
	v_add_f32_e32 v89, 1.0, v89
	v_rcp_f32_e32 v88, v88
	v_rcp_f32_e32 v89, v89
	s_nop 0
	v_pk_mul_f32 v[82:83], v[82:83], v[88:89]
	s_nop 0
	v_pk_mul_f32 v[88:89], v[84:85], v[82:83]
	v_cvt_pk_bf16_f32 v84, v86, v87
	v_mad_i64_i32 v[86:87], s[46:47], v94, s39, v[118:119]
	v_cvt_pk_bf16_f32 v82, v90, v91
	v_cvt_pk_bf16_f32 v83, v92, v93
	v_cvt_pk_bf16_f32 v85, v88, v89
	v_lshl_add_u64 v[86:87], v[86:87], 0, v[120:121]
	global_store_dwordx4 v[86:87], v[82:85], off
	s_nop 1
	v_mul_f32_e32 v82, 0xbfb8aa3b, v78
	v_mul_f32_e32 v83, 0xbfb8aa3b, v79
	v_exp_f32_e32 v82, v82
	v_exp_f32_e32 v83, v83
	v_add_f32_e32 v82, 1.0, v82
	v_add_f32_e32 v83, 1.0, v83
	v_rcp_f32_e32 v82, v82
	v_rcp_f32_e32 v83, v83
	s_nop 0
	v_pk_mul_f32 v[78:79], v[78:79], v[82:83]
	s_nop 0
	v_pk_mul_f32 v[74:75], v[74:75], v[78:79]
	v_pk_mul_f32 v[78:79], v[80:81], v[148:149] op_sel_hi:[1,0]
	s_nop 0
	v_mul_f32_e32 v80, 0xbfb8aa3b, v78
	v_mul_f32_e32 v81, 0xbfb8aa3b, v79
	v_exp_f32_e32 v80, v80
	v_exp_f32_e32 v81, v81
	v_add_f32_e32 v80, 1.0, v80
	v_add_f32_e32 v81, 1.0, v81
	v_rcp_f32_e32 v80, v80
	v_rcp_f32_e32 v81, v81
	s_nop 0
	v_pk_mul_f32 v[78:79], v[78:79], v[80:81]
	s_nop 0
	v_pk_mul_f32 v[76:77], v[76:77], v[78:79]
	v_mul_f32_e32 v78, 0xbfb8aa3b, v70
	v_mul_f32_e32 v79, 0xbfb8aa3b, v71
	v_exp_f32_e32 v78, v78
	v_exp_f32_e32 v79, v79
	v_add_f32_e32 v78, 1.0, v78
	v_add_f32_e32 v79, 1.0, v79
	v_rcp_f32_e32 v78, v78
	v_rcp_f32_e32 v79, v79
	s_nop 0
	v_pk_mul_f32 v[70:71], v[70:71], v[78:79]
	s_nop 0
	v_pk_mul_f32 v[70:71], v[66:67], v[70:71]
	v_pk_mul_f32 v[66:67], v[72:73], v[148:149] op_sel_hi:[1,0]
	v_or_b32_e32 v78, 48, v153
	v_mul_f32_e32 v72, 0xbfb8aa3b, v66
	v_mul_f32_e32 v73, 0xbfb8aa3b, v67
	v_exp_f32_e32 v72, v72
	v_exp_f32_e32 v73, v73
	v_add_f32_e32 v72, 1.0, v72
	v_add_f32_e32 v73, 1.0, v73
	v_rcp_f32_e32 v72, v72
	v_rcp_f32_e32 v73, v73
	s_nop 0
	v_pk_mul_f32 v[66:67], v[66:67], v[72:73]
	s_nop 0
	v_pk_mul_f32 v[72:73], v[68:69], v[66:67]
	v_cvt_pk_bf16_f32 v68, v70, v71
	v_mad_i64_i32 v[70:71], s[46:47], v78, s39, v[118:119]
	v_cvt_pk_bf16_f32 v66, v74, v75
	v_cvt_pk_bf16_f32 v67, v76, v77
	v_cvt_pk_bf16_f32 v69, v72, v73
	v_lshl_add_u64 v[70:71], v[70:71], 0, v[120:121]
	global_store_dwordx4 v[70:71], v[66:69], off
	s_nop 1
	v_mul_f32_e32 v66, 0xbfb8aa3b, v62
	v_mul_f32_e32 v67, 0xbfb8aa3b, v63
	v_exp_f32_e32 v66, v66
	v_exp_f32_e32 v67, v67
	v_add_u32_e32 v68, 0x80, v153
	v_add_f32_e32 v66, 1.0, v66
	v_add_f32_e32 v67, 1.0, v67
	v_rcp_f32_e32 v66, v66
	v_rcp_f32_e32 v67, v67
	s_nop 0
	v_pk_mul_f32 v[62:63], v[62:63], v[66:67]
	s_nop 0
	v_pk_mul_f32 v[58:59], v[58:59], v[62:63]
	v_pk_mul_f32 v[62:63], v[64:65], v[146:147] op_sel_hi:[1,0]
	s_nop 0
	v_mul_f32_e32 v64, 0xbfb8aa3b, v62
	v_mul_f32_e32 v65, 0xbfb8aa3b, v63
	v_exp_f32_e32 v64, v64
	v_exp_f32_e32 v65, v65
	v_add_f32_e32 v64, 1.0, v64
; __device__ __forceinline__ unsigned pk2(float lo, float hi) { f32x2 v = {lo, hi}; bf16x2_t b = __builtin_convertvector(v, bf16x2_t); return __builtin_bit_cast(unsigned, b); }
; #define PG8_WAIT_V(n) asm volatile("s_waitcnt vmcnt(" #n ")" ::: "memory")
; #define PG8_BAR __builtin_amdgcn_s_barrier()
;     __device__ __forceinline__ void operator()(const AccT& acc, const Unit& u, int wr, int wc, int fr, int fq) const {
;     ...
; #pragma unroll
;         for (int ai = 0; ai < 2; ++ai)
; #pragma unroll
;             for (int m = 0; m < 4; ++m) {
;                 const int row = row0 + ai * HALF + m * 16;
;                 const float rs = rsv[ai * 4 + m];
;                 float v[8];
; #pragma unroll
;                 for (int n = 0; n < 2; ++n)
; #pragma unroll
;                     for (int j = 0; j < 4; ++j) {
;                         const float g = acc[ai][0][m][n][j] * rs, up = acc[ai][1][m][n][j] * rs;
;                         const float sg = __builtin_amdgcn_rcpf(1.0f + __builtin_amdgcn_exp2f(-g * LOG2E));
;                         v[4 * n + j] = g * sg * up;
;                     }
;                 u32x4 w; w.x = pk2(v[0], v[1]); w.y = pk2(v[2], v[3]); w.z = pk2(v[4], v[5]); w.w = pk2(v[6], v[7]);
;                 *(u32x4*)(mid + (size_t)row * FF + col0) = w;
; template <class Epi>
; __device__ __forceinline__ void gemm_phase(LAS unsigned char* lds, const Gemm g, const StaticOrder& S, const Epi& E) {
;     ...
;         if (!has_next) break;
; #pragma unroll
;         for (int a = 0; a < 2; ++a)
; #pragma unroll
;             for (int b = 0; b < 2; ++b)
; #pragma unroll
;                 for (int m = 0; m < 4; ++m)
; #pragma unroll
;                     for (int n = 0; n < 2; ++n) acc[a][b][m][n] = (f32x4){0.f, 0.f, 0.f, 0.f};
;         cur = nxt; cA = nA; cB = nB; ++ui;
;     }
;     PG8_WAIT_V(0);
;     if (wr == 0) PG8_BAR;
;     PG8_BAR;
	v_add_f32_e32 v65, 1.0, v65
	v_rcp_f32_e32 v64, v64
	v_rcp_f32_e32 v65, v65
	s_nop 0
	v_pk_mul_f32 v[62:63], v[62:63], v[64:65]
	s_nop 0
	v_pk_mul_f32 v[60:61], v[60:61], v[62:63]
	v_mul_f32_e32 v62, 0xbfb8aa3b, v54
	v_mul_f32_e32 v63, 0xbfb8aa3b, v55
	v_exp_f32_e32 v62, v62
	v_exp_f32_e32 v63, v63
	v_add_f32_e32 v62, 1.0, v62
	v_add_f32_e32 v63, 1.0, v63
	v_rcp_f32_e32 v62, v62
	v_rcp_f32_e32 v63, v63
	s_nop 0
	v_pk_mul_f32 v[54:55], v[54:55], v[62:63]
	s_nop 0
	v_pk_mul_f32 v[54:55], v[50:51], v[54:55]
	v_pk_mul_f32 v[50:51], v[56:57], v[146:147] op_sel_hi:[1,0]
	s_nop 0
	v_mul_f32_e32 v56, 0xbfb8aa3b, v50
	v_mul_f32_e32 v57, 0xbfb8aa3b, v51
	v_exp_f32_e32 v56, v56
	v_exp_f32_e32 v57, v57
	v_add_f32_e32 v56, 1.0, v56
	v_add_f32_e32 v57, 1.0, v57
	v_rcp_f32_e32 v56, v56
	v_rcp_f32_e32 v57, v57
	s_nop 0
	v_pk_mul_f32 v[50:51], v[50:51], v[56:57]
	s_nop 0
	v_pk_mul_f32 v[56:57], v[52:53], v[50:51]
	v_cvt_pk_bf16_f32 v52, v54, v55
	v_mad_i64_i32 v[54:55], s[46:47], v68, s39, v[118:119]
	v_cvt_pk_bf16_f32 v50, v58, v59
	v_cvt_pk_bf16_f32 v51, v60, v61
	v_cvt_pk_bf16_f32 v53, v56, v57
	v_lshl_add_u64 v[54:55], v[54:55], 0, v[120:121]
	global_store_dwordx4 v[54:55], v[50:53], off
	s_nop 1
	v_mul_f32_e32 v50, 0xbfb8aa3b, v46
	v_mul_f32_e32 v51, 0xbfb8aa3b, v47
	v_exp_f32_e32 v50, v50
	v_exp_f32_e32 v51, v51
	v_add_f32_e32 v50, 1.0, v50
	v_add_f32_e32 v51, 1.0, v51
	v_rcp_f32_e32 v50, v50
	v_rcp_f32_e32 v51, v51
	s_nop 0
	v_pk_mul_f32 v[46:47], v[46:47], v[50:51]
	s_nop 0
	v_pk_mul_f32 v[42:43], v[42:43], v[46:47]
	v_pk_mul_f32 v[46:47], v[48:49], v[144:145] op_sel_hi:[1,0]
	s_nop 0
	v_mul_f32_e32 v48, 0xbfb8aa3b, v46
	v_mul_f32_e32 v49, 0xbfb8aa3b, v47
	v_exp_f32_e32 v48, v48
	v_exp_f32_e32 v49, v49
	v_add_f32_e32 v48, 1.0, v48
	v_add_f32_e32 v49, 1.0, v49
	v_rcp_f32_e32 v48, v48
	v_rcp_f32_e32 v49, v49
	s_nop 0
	v_pk_mul_f32 v[46:47], v[46:47], v[48:49]
	s_nop 0
	v_pk_mul_f32 v[44:45], v[44:45], v[46:47]
	v_mul_f32_e32 v46, 0xbfb8aa3b, v38
	v_mul_f32_e32 v47, 0xbfb8aa3b, v39
	v_exp_f32_e32 v46, v46
	v_exp_f32_e32 v47, v47
	v_add_f32_e32 v46, 1.0, v46
	v_add_f32_e32 v47, 1.0, v47
	v_rcp_f32_e32 v46, v46
	v_rcp_f32_e32 v47, v47
	s_nop 0
	v_pk_mul_f32 v[38:39], v[38:39], v[46:47]
	s_nop 0
	v_pk_mul_f32 v[38:39], v[34:35], v[38:39]
	v_pk_mul_f32 v[34:35], v[40:41], v[144:145] op_sel_hi:[1,0]
	v_add_u32_e32 v46, 0x90, v153
	v_mul_f32_e32 v40, 0xbfb8aa3b, v34
	v_mul_f32_e32 v41, 0xbfb8aa3b, v35
	v_exp_f32_e32 v40, v40
	v_exp_f32_e32 v41, v41
	v_add_f32_e32 v40, 1.0, v40
	v_add_f32_e32 v41, 1.0, v41
	v_rcp_f32_e32 v40, v40
	v_rcp_f32_e32 v41, v41
	s_nop 0
	v_pk_mul_f32 v[34:35], v[34:35], v[40:41]
	s_nop 0
	v_pk_mul_f32 v[40:41], v[36:37], v[34:35]
	v_cvt_pk_bf16_f32 v36, v38, v39
	v_mad_i64_i32 v[38:39], s[46:47], v46, s39, v[118:119]
	v_cvt_pk_bf16_f32 v34, v42, v43
	v_cvt_pk_bf16_f32 v35, v44, v45
	v_cvt_pk_bf16_f32 v37, v40, v41
	v_lshl_add_u64 v[38:39], v[38:39], 0, v[120:121]
	global_store_dwordx4 v[38:39], v[34:37], off
	s_nop 1
	v_mul_f32_e32 v34, 0xbfb8aa3b, v30
	v_mul_f32_e32 v35, 0xbfb8aa3b, v31
	v_exp_f32_e32 v34, v34
	v_exp_f32_e32 v35, v35
	v_add_f32_e32 v34, 1.0, v34
	v_add_f32_e32 v35, 1.0, v35
	v_rcp_f32_e32 v34, v34
	v_rcp_f32_e32 v35, v35
	s_nop 0
	v_pk_mul_f32 v[30:31], v[30:31], v[34:35]
	s_nop 0
	v_pk_mul_f32 v[26:27], v[26:27], v[30:31]
	v_pk_mul_f32 v[30:31], v[32:33], v[142:143] op_sel_hi:[1,0]
	s_nop 0
	v_mul_f32_e32 v32, 0xbfb8aa3b, v30
	v_mul_f32_e32 v33, 0xbfb8aa3b, v31
	v_exp_f32_e32 v32, v32
	v_exp_f32_e32 v33, v33
	v_add_f32_e32 v32, 1.0, v32
	v_add_f32_e32 v33, 1.0, v33
	v_rcp_f32_e32 v32, v32
	v_rcp_f32_e32 v33, v33
	s_nop 0
	v_pk_mul_f32 v[30:31], v[30:31], v[32:33]
	s_nop 0
	v_pk_mul_f32 v[28:29], v[28:29], v[30:31]
	v_mul_f32_e32 v30, 0xbfb8aa3b, v22
	v_mul_f32_e32 v31, 0xbfb8aa3b, v23
	v_exp_f32_e32 v30, v30
	v_exp_f32_e32 v31, v31
	v_add_f32_e32 v30, 1.0, v30
	v_add_f32_e32 v31, 1.0, v31
	v_rcp_f32_e32 v30, v30
	v_rcp_f32_e32 v31, v31
	s_nop 0
	v_pk_mul_f32 v[22:23], v[22:23], v[30:31]
	s_nop 0
	v_pk_mul_f32 v[22:23], v[18:19], v[22:23]
	v_pk_mul_f32 v[18:19], v[24:25], v[142:143] op_sel_hi:[1,0]
	v_add_u32_e32 v30, 0xa0, v153
	v_mul_f32_e32 v24, 0xbfb8aa3b, v18
	v_mul_f32_e32 v25, 0xbfb8aa3b, v19
	v_exp_f32_e32 v24, v24
	v_exp_f32_e32 v25, v25
	v_add_f32_e32 v24, 1.0, v24
	v_add_f32_e32 v25, 1.0, v25
	v_rcp_f32_e32 v24, v24
	v_rcp_f32_e32 v25, v25
	s_nop 0
	v_pk_mul_f32 v[18:19], v[18:19], v[24:25]
	s_nop 0
	v_pk_mul_f32 v[24:25], v[20:21], v[18:19]
	v_cvt_pk_bf16_f32 v20, v22, v23
	v_mad_i64_i32 v[22:23], s[46:47], v30, s39, v[118:119]
	v_cvt_pk_bf16_f32 v18, v26, v27
	v_cvt_pk_bf16_f32 v19, v28, v29
	v_cvt_pk_bf16_f32 v21, v24, v25
	v_lshl_add_u64 v[22:23], v[22:23], 0, v[120:121]
	global_store_dwordx4 v[22:23], v[18:21], off
	s_nop 1
	v_mul_f32_e32 v18, 0xbfb8aa3b, v14
	v_mul_f32_e32 v19, 0xbfb8aa3b, v15
	v_exp_f32_e32 v18, v18
	v_exp_f32_e32 v19, v19
	v_add_f32_e32 v18, 1.0, v18
	v_add_f32_e32 v19, 1.0, v19
	v_rcp_f32_e32 v18, v18
	v_rcp_f32_e32 v19, v19
	s_nop 0
	v_pk_mul_f32 v[14:15], v[14:15], v[18:19]
	s_nop 0
	v_pk_mul_f32 v[10:11], v[10:11], v[14:15]
	v_pk_mul_f32 v[14:15], v[16:17], v[140:141] op_sel_hi:[1,0]
	s_nop 0
	v_mul_f32_e32 v16, 0xbfb8aa3b, v14
	v_mul_f32_e32 v17, 0xbfb8aa3b, v15
	v_exp_f32_e32 v16, v16
	v_exp_f32_e32 v17, v17
	v_add_f32_e32 v16, 1.0, v16
	v_add_f32_e32 v17, 1.0, v17
	v_rcp_f32_e32 v16, v16
	v_rcp_f32_e32 v17, v17
	s_nop 0
	v_pk_mul_f32 v[14:15], v[14:15], v[16:17]
	s_nop 0
	v_pk_mul_f32 v[12:13], v[12:13], v[14:15]
	v_mul_f32_e32 v14, 0xbfb8aa3b, v6
	v_mul_f32_e32 v15, 0xbfb8aa3b, v7
	v_exp_f32_e32 v14, v14
	v_exp_f32_e32 v15, v15
	v_add_f32_e32 v14, 1.0, v14
	v_add_f32_e32 v15, 1.0, v15
	v_rcp_f32_e32 v14, v14
	v_rcp_f32_e32 v15, v15
	s_nop 0
	v_pk_mul_f32 v[6:7], v[6:7], v[14:15]
	s_nop 0
	v_pk_mul_f32 v[6:7], v[2:3], v[6:7]
	v_pk_mul_f32 v[2:3], v[8:9], v[140:141] op_sel_hi:[1,0]
	v_add_u32_e32 v14, 0xb0, v153
	v_mul_f32_e32 v8, 0xbfb8aa3b, v2
	v_mul_f32_e32 v9, 0xbfb8aa3b, v3
	v_exp_f32_e32 v8, v8
	v_exp_f32_e32 v9, v9
	v_add_f32_e32 v8, 1.0, v8
	v_add_f32_e32 v9, 1.0, v9
	v_rcp_f32_e32 v8, v8
	v_rcp_f32_e32 v9, v9
	s_nop 0
	v_pk_mul_f32 v[2:3], v[2:3], v[8:9]
	s_nop 0
	v_pk_mul_f32 v[8:9], v[4:5], v[2:3]
	v_cvt_pk_bf16_f32 v4, v6, v7
	v_mad_i64_i32 v[6:7], s[46:47], v14, s39, v[118:119]
	v_cvt_pk_bf16_f32 v2, v10, v11
	v_cvt_pk_bf16_f32 v3, v12, v13
	v_cvt_pk_bf16_f32 v5, v8, v9
	v_lshl_add_u64 v[6:7], v[6:7], 0, v[120:121]
	s_mov_b64 s[46:47], s[42:43]
	global_store_dwordx4 v[6:7], v[2:5], off
	s_cbranch_vccz .LBB0_87
	s_waitcnt vmcnt(0)
	s_cmpk_gt_u32 s52, 0xff
	s_cbranch_scc1 .LBB0_94
	s_barrier
